# E9: GEMM K-loops: the 96 s_nop pads between s_mov m0 and the LDS-DMA loads replaced by moved ds_reads (or deleted where m0 was written earlier); on top of Y2
# speedup vs baseline: 1.0006x; 1.0006x over previous
.LBB0_287:
	ds_read_b128 v[136:139], v2
	ds_read_b128 v[140:143], v2 offset:1024
	ds_read_b128 v[144:147], v2 offset:2048
	ds_read_b128 v[148:151], v2 offset:3072
	ds_read_b128 v[152:155], v132
	ds_read_b128 v[156:159], v132 offset:1024
	ds_read_b128 v[160:163], v132 offset:2048
	ds_read_b128 v[164:167], v132 offset:3072
	s_cmp_eq_u32 s82, s72
	s_cselect_b32 s17, s51, s53
	s_cselect_b32 s16, s50, s52
	s_cselect_b32 s21, s15, s27
	s_cselect_b32 s20, s14, s26
	s_add_u32 s8, s26, 0xffffff80
	s_addc_u32 s9, s27, -1
	s_mov_b32 m0, s42
	s_mov_b64 s[18:19], s[8:9]
	ds_read_b128 v[168:171], v199 offset:8192
	ds_read_b128 v[172:175], v199 offset:9216
	ds_read_b128 v[176:179], v199 offset:10240
	ds_read_b128 v[180:183], v199 offset:11264
	ds_read_b128 v[184:187], v199 offset:12288
	ds_read_b128 v[188:191], v199 offset:13312
	ds_read_b128 v[202:205], v199 offset:14336
	ds_read_b128 v[206:209], v199 offset:15360
	s_add_u32 s8, s8, s54
	global_load_lds_dwordx4 v194, s[18:19]
	s_mov_b32 m0, s43
	s_addc_u32 s9, s9, s55
	global_load_lds_dwordx4 v195, s[18:19]
	s_mov_b32 m0, s44
	s_add_u32 s18, s16, 0x80
	global_load_lds_dwordx4 v194, s[8:9]
	s_mov_b32 m0, s45
	s_addc_u32 s19, s17, 0
	global_load_lds_dwordx4 v195, s[8:9]
	s_waitcnt vmcnt(8)
	s_waitcnt lgkmcnt(0)
	s_barrier
	s_setprio 1
	s_waitcnt lgkmcnt(0)
	v_mfma_f32_16x16x32_bf16 v[4:7], v[136:139], v[168:171], v[4:7]
	v_mfma_f32_16x16x32_bf16 v[4:7], v[140:143], v[172:175], v[4:7]
	v_mfma_f32_16x16x32_bf16 v[8:11], v[144:147], v[168:171], v[8:11]
	v_mfma_f32_16x16x32_bf16 v[8:11], v[148:151], v[172:175], v[8:11]
	v_mfma_f32_16x16x32_bf16 v[12:15], v[136:139], v[176:179], v[12:15]
	v_mfma_f32_16x16x32_bf16 v[12:15], v[140:143], v[180:183], v[12:15]
	v_mfma_f32_16x16x32_bf16 v[16:19], v[144:147], v[176:179], v[16:19]
	v_mfma_f32_16x16x32_bf16 v[16:19], v[148:151], v[180:183], v[16:19]
	v_mfma_f32_16x16x32_bf16 v[20:23], v[136:139], v[184:187], v[20:23]
	v_mfma_f32_16x16x32_bf16 v[20:23], v[140:143], v[188:191], v[20:23]
	v_mfma_f32_16x16x32_bf16 v[24:27], v[144:147], v[184:187], v[24:27]
	v_mfma_f32_16x16x32_bf16 v[24:27], v[148:151], v[188:191], v[24:27]
	v_mfma_f32_16x16x32_bf16 v[28:31], v[136:139], v[202:205], v[28:31]
	v_mfma_f32_16x16x32_bf16 v[28:31], v[140:143], v[206:209], v[28:31]
	v_mfma_f32_16x16x32_bf16 v[32:35], v[144:147], v[202:205], v[32:35]
	v_mfma_f32_16x16x32_bf16 v[32:35], v[148:151], v[206:209], v[32:35]
	s_setprio 0
	s_setprio 1
	v_mfma_f32_16x16x32_bf16 v[36:39], v[152:155], v[168:171], v[36:39]
	v_mfma_f32_16x16x32_bf16 v[36:39], v[156:159], v[172:175], v[36:39]
	v_mfma_f32_16x16x32_bf16 v[40:43], v[160:163], v[168:171], v[40:43]
	v_mfma_f32_16x16x32_bf16 v[40:43], v[164:167], v[172:175], v[40:43]
	v_mfma_f32_16x16x32_bf16 v[44:47], v[152:155], v[176:179], v[44:47]
	v_mfma_f32_16x16x32_bf16 v[44:47], v[156:159], v[180:183], v[44:47]
	v_mfma_f32_16x16x32_bf16 v[48:51], v[160:163], v[176:179], v[48:51]
	v_mfma_f32_16x16x32_bf16 v[48:51], v[164:167], v[180:183], v[48:51]
	v_mfma_f32_16x16x32_bf16 v[52:55], v[152:155], v[184:187], v[52:55]
	v_mfma_f32_16x16x32_bf16 v[52:55], v[156:159], v[188:191], v[52:55]
	v_mfma_f32_16x16x32_bf16 v[56:59], v[160:163], v[184:187], v[56:59]
	v_mfma_f32_16x16x32_bf16 v[56:59], v[164:167], v[188:191], v[56:59]
	v_mfma_f32_16x16x32_bf16 v[60:63], v[152:155], v[202:205], v[60:63]
	v_mfma_f32_16x16x32_bf16 v[60:63], v[156:159], v[206:209], v[60:63]
	v_mfma_f32_16x16x32_bf16 v[64:67], v[160:163], v[202:205], v[64:67]
	v_mfma_f32_16x16x32_bf16 v[64:67], v[164:167], v[206:209], v[64:67]
	s_setprio 0
	s_barrier
	s_mov_b32 m0, s46
	s_mov_b64 s[8:9], s[16:17]
	ds_read_b128 v[168:171], v199 offset:24576
	ds_read_b128 v[172:175], v199 offset:25600
	ds_read_b128 v[176:179], v199 offset:26624
	ds_read_b128 v[180:183], v199 offset:27648
	ds_read_b128 v[184:187], v199 offset:28672
	global_load_lds_dwordx4 v201, s[8:9]
	s_mov_b32 m0, s47
	ds_read_b128 v[188:191], v199 offset:29696
	global_load_lds_dwordx4 v200, s[8:9]
	s_add_u32 s8, s16, s54
	s_addc_u32 s9, s17, s55
	s_mov_b32 m0, s30
	ds_read_b128 v[202:205], v199 offset:30720
	global_load_lds_dwordx4 v201, s[8:9]
	s_mov_b32 m0, s31
	ds_read_b128 v[206:209], v199 offset:31744
	global_load_lds_dwordx4 v200, s[8:9]
	s_waitcnt vmcnt(6)
	s_waitcnt lgkmcnt(0)
	s_barrier
	s_setprio 1
	s_waitcnt lgkmcnt(0)
	v_mfma_f32_16x16x32_bf16 v[68:71], v[136:139], v[168:171], v[68:71]
	v_mfma_f32_16x16x32_bf16 v[68:71], v[140:143], v[172:175], v[68:71]
	v_mfma_f32_16x16x32_bf16 v[72:75], v[144:147], v[168:171], v[72:75]
	v_mfma_f32_16x16x32_bf16 v[72:75], v[148:151], v[172:175], v[72:75]
	v_mfma_f32_16x16x32_bf16 v[76:79], v[136:139], v[176:179], v[76:79]
	v_mfma_f32_16x16x32_bf16 v[76:79], v[140:143], v[180:183], v[76:79]
	v_mfma_f32_16x16x32_bf16 v[80:83], v[144:147], v[176:179], v[80:83]
	v_mfma_f32_16x16x32_bf16 v[80:83], v[148:151], v[180:183], v[80:83]
	v_mfma_f32_16x16x32_bf16 v[84:87], v[136:139], v[184:187], v[84:87]
	v_mfma_f32_16x16x32_bf16 v[84:87], v[140:143], v[188:191], v[84:87]
	v_mfma_f32_16x16x32_bf16 v[88:91], v[144:147], v[184:187], v[88:91]
	v_mfma_f32_16x16x32_bf16 v[88:91], v[148:151], v[188:191], v[88:91]
	v_mfma_f32_16x16x32_bf16 v[92:95], v[136:139], v[202:205], v[92:95]
	v_mfma_f32_16x16x32_bf16 v[92:95], v[140:143], v[206:209], v[92:95]
	v_mfma_f32_16x16x32_bf16 v[96:99], v[144:147], v[202:205], v[96:99]
	v_mfma_f32_16x16x32_bf16 v[96:99], v[148:151], v[206:209], v[96:99]
	s_setprio 0
	s_setprio 1
	v_mfma_f32_16x16x32_bf16 v[100:103], v[152:155], v[168:171], v[100:103]
	v_mfma_f32_16x16x32_bf16 v[100:103], v[156:159], v[172:175], v[100:103]
	v_mfma_f32_16x16x32_bf16 v[104:107], v[160:163], v[168:171], v[104:107]
	v_mfma_f32_16x16x32_bf16 v[104:107], v[164:167], v[172:175], v[104:107]
	v_mfma_f32_16x16x32_bf16 v[108:111], v[152:155], v[176:179], v[108:111]
	v_mfma_f32_16x16x32_bf16 v[108:111], v[156:159], v[180:183], v[108:111]
	v_mfma_f32_16x16x32_bf16 v[112:115], v[160:163], v[176:179], v[112:115]
	v_mfma_f32_16x16x32_bf16 v[112:115], v[164:167], v[180:183], v[112:115]
	v_mfma_f32_16x16x32_bf16 v[116:119], v[152:155], v[184:187], v[116:119]
	v_mfma_f32_16x16x32_bf16 v[116:119], v[156:159], v[188:191], v[116:119]
	v_mfma_f32_16x16x32_bf16 v[120:123], v[160:163], v[184:187], v[120:123]
	v_mfma_f32_16x16x32_bf16 v[120:123], v[164:167], v[188:191], v[120:123]
	v_mfma_f32_16x16x32_bf16 v[124:127], v[152:155], v[202:205], v[124:127]
	v_mfma_f32_16x16x32_bf16 v[124:127], v[156:159], v[206:209], v[124:127]
	v_mfma_f32_16x16x32_bf16 v[128:131], v[160:163], v[202:205], v[128:131]
	v_mfma_f32_16x16x32_bf16 v[128:131], v[164:167], v[206:209], v[128:131]
	s_setprio 0
	s_barrier
	ds_read_b128 v[136:139], v133
	ds_read_b128 v[140:143], v133 offset:1024
	ds_read_b128 v[144:147], v133 offset:2048
	ds_read_b128 v[148:151], v133 offset:3072
	ds_read_b128 v[152:155], v134
	ds_read_b128 v[156:159], v134 offset:1024
	ds_read_b128 v[160:163], v134 offset:2048
	ds_read_b128 v[164:167], v134 offset:3072
	s_mov_b32 m0, s85
	s_mov_b64 s[8:9], s[20:21]
	ds_read_b128 v[168:171], v199 offset:40960
	ds_read_b128 v[172:175], v199 offset:41984
	ds_read_b128 v[176:179], v199 offset:43008
	ds_read_b128 v[180:183], v199 offset:44032
	ds_read_b128 v[184:187], v199 offset:45056
	global_load_lds_dwordx4 v194, s[8:9]
	s_mov_b32 m0, s86
	ds_read_b128 v[188:191], v199 offset:46080
	global_load_lds_dwordx4 v195, s[8:9]
	s_add_u32 s8, s20, s54
	s_addc_u32 s9, s21, s55
	s_mov_b32 m0, s87
	ds_read_b128 v[202:205], v199 offset:47104
	global_load_lds_dwordx4 v194, s[8:9]
	s_mov_b32 m0, s88
	ds_read_b128 v[206:209], v199 offset:48128
	global_load_lds_dwordx4 v195, s[8:9]
	s_waitcnt vmcnt(8)
	s_waitcnt lgkmcnt(0)
	s_barrier
	s_setprio 1
	s_waitcnt lgkmcnt(0)
	v_mfma_f32_16x16x32_bf16 v[4:7], v[136:139], v[168:171], v[4:7]
	v_mfma_f32_16x16x32_bf16 v[4:7], v[140:143], v[172:175], v[4:7]
	v_mfma_f32_16x16x32_bf16 v[8:11], v[144:147], v[168:171], v[8:11]
	v_mfma_f32_16x16x32_bf16 v[8:11], v[148:151], v[172:175], v[8:11]
	v_mfma_f32_16x16x32_bf16 v[12:15], v[136:139], v[176:179], v[12:15]
	v_mfma_f32_16x16x32_bf16 v[12:15], v[140:143], v[180:183], v[12:15]
	v_mfma_f32_16x16x32_bf16 v[16:19], v[144:147], v[176:179], v[16:19]
	v_mfma_f32_16x16x32_bf16 v[16:19], v[148:151], v[180:183], v[16:19]
	v_mfma_f32_16x16x32_bf16 v[20:23], v[136:139], v[184:187], v[20:23]
	v_mfma_f32_16x16x32_bf16 v[20:23], v[140:143], v[188:191], v[20:23]
	v_mfma_f32_16x16x32_bf16 v[24:27], v[144:147], v[184:187], v[24:27]
	v_mfma_f32_16x16x32_bf16 v[24:27], v[148:151], v[188:191], v[24:27]
	v_mfma_f32_16x16x32_bf16 v[28:31], v[136:139], v[202:205], v[28:31]
	v_mfma_f32_16x16x32_bf16 v[28:31], v[140:143], v[206:209], v[28:31]
	v_mfma_f32_16x16x32_bf16 v[32:35], v[144:147], v[202:205], v[32:35]
	v_mfma_f32_16x16x32_bf16 v[32:35], v[148:151], v[206:209], v[32:35]
	s_setprio 0
	s_setprio 1
	v_mfma_f32_16x16x32_bf16 v[36:39], v[152:155], v[168:171], v[36:39]
	v_mfma_f32_16x16x32_bf16 v[36:39], v[156:159], v[172:175], v[36:39]
	v_mfma_f32_16x16x32_bf16 v[40:43], v[160:163], v[168:171], v[40:43]
	v_mfma_f32_16x16x32_bf16 v[40:43], v[164:167], v[172:175], v[40:43]
	v_mfma_f32_16x16x32_bf16 v[44:47], v[152:155], v[176:179], v[44:47]
	v_mfma_f32_16x16x32_bf16 v[44:47], v[156:159], v[180:183], v[44:47]
	v_mfma_f32_16x16x32_bf16 v[48:51], v[160:163], v[176:179], v[48:51]
	v_mfma_f32_16x16x32_bf16 v[48:51], v[164:167], v[180:183], v[48:51]
	v_mfma_f32_16x16x32_bf16 v[52:55], v[152:155], v[184:187], v[52:55]
	v_mfma_f32_16x16x32_bf16 v[52:55], v[156:159], v[188:191], v[52:55]
	v_mfma_f32_16x16x32_bf16 v[56:59], v[160:163], v[184:187], v[56:59]
	v_mfma_f32_16x16x32_bf16 v[56:59], v[164:167], v[188:191], v[56:59]
	v_mfma_f32_16x16x32_bf16 v[60:63], v[152:155], v[202:205], v[60:63]
	v_mfma_f32_16x16x32_bf16 v[60:63], v[156:159], v[206:209], v[60:63]
	v_mfma_f32_16x16x32_bf16 v[64:67], v[160:163], v[202:205], v[64:67]
	v_mfma_f32_16x16x32_bf16 v[64:67], v[164:167], v[206:209], v[64:67]
	s_setprio 0
	s_barrier
	s_mov_b32 m0, s48
	s_mov_b64 s[8:9], s[18:19]
	ds_read_b128 v[168:171], v199 offset:57344
	ds_read_b128 v[172:175], v199 offset:58368
	ds_read_b128 v[176:179], v199 offset:59392
	ds_read_b128 v[180:183], v199 offset:60416
	ds_read_b128 v[184:187], v199 offset:61440
	global_load_lds_dwordx4 v201, s[8:9]
	s_mov_b32 m0, s49
	ds_read_b128 v[188:191], v199 offset:62464
	global_load_lds_dwordx4 v200, s[8:9]
	s_add_u32 s8, s18, s54
	s_addc_u32 s9, s19, s55
	s_mov_b32 m0, s28
	ds_read_b128 v[202:205], v199 offset:63488
	global_load_lds_dwordx4 v201, s[8:9]
	s_mov_b32 m0, s29
	ds_read_b128 v[206:209], v199 offset:64512
	global_load_lds_dwordx4 v200, s[8:9]
	s_waitcnt vmcnt(6)
	s_waitcnt lgkmcnt(0)
	s_barrier
	s_setprio 1
	s_waitcnt lgkmcnt(0)
	v_mfma_f32_16x16x32_bf16 v[68:71], v[136:139], v[168:171], v[68:71]
	v_mfma_f32_16x16x32_bf16 v[68:71], v[140:143], v[172:175], v[68:71]
	v_mfma_f32_16x16x32_bf16 v[72:75], v[144:147], v[168:171], v[72:75]
	v_mfma_f32_16x16x32_bf16 v[72:75], v[148:151], v[172:175], v[72:75]
	v_mfma_f32_16x16x32_bf16 v[76:79], v[136:139], v[176:179], v[76:79]
	v_mfma_f32_16x16x32_bf16 v[76:79], v[140:143], v[180:183], v[76:79]
	v_mfma_f32_16x16x32_bf16 v[80:83], v[144:147], v[176:179], v[80:83]
	v_mfma_f32_16x16x32_bf16 v[80:83], v[148:151], v[180:183], v[80:83]
	v_mfma_f32_16x16x32_bf16 v[84:87], v[136:139], v[184:187], v[84:87]
	v_mfma_f32_16x16x32_bf16 v[84:87], v[140:143], v[188:191], v[84:87]
	v_mfma_f32_16x16x32_bf16 v[88:91], v[144:147], v[184:187], v[88:91]
	v_mfma_f32_16x16x32_bf16 v[88:91], v[148:151], v[188:191], v[88:91]
	v_mfma_f32_16x16x32_bf16 v[92:95], v[136:139], v[202:205], v[92:95]
	v_mfma_f32_16x16x32_bf16 v[92:95], v[140:143], v[206:209], v[92:95]
	v_mfma_f32_16x16x32_bf16 v[96:99], v[144:147], v[202:205], v[96:99]
	v_mfma_f32_16x16x32_bf16 v[96:99], v[148:151], v[206:209], v[96:99]
	s_setprio 0
	s_setprio 1
	v_mfma_f32_16x16x32_bf16 v[100:103], v[152:155], v[168:171], v[100:103]
	v_mfma_f32_16x16x32_bf16 v[100:103], v[156:159], v[172:175], v[100:103]
	v_mfma_f32_16x16x32_bf16 v[104:107], v[160:163], v[168:171], v[104:107]
	v_mfma_f32_16x16x32_bf16 v[104:107], v[164:167], v[172:175], v[104:107]
	v_mfma_f32_16x16x32_bf16 v[108:111], v[152:155], v[176:179], v[108:111]
	v_mfma_f32_16x16x32_bf16 v[108:111], v[156:159], v[180:183], v[108:111]
	v_mfma_f32_16x16x32_bf16 v[112:115], v[160:163], v[176:179], v[112:115]
	v_mfma_f32_16x16x32_bf16 v[112:115], v[164:167], v[180:183], v[112:115]
	v_mfma_f32_16x16x32_bf16 v[116:119], v[152:155], v[184:187], v[116:119]
	v_mfma_f32_16x16x32_bf16 v[116:119], v[156:159], v[188:191], v[116:119]
	v_mfma_f32_16x16x32_bf16 v[120:123], v[160:163], v[184:187], v[120:123]
	v_mfma_f32_16x16x32_bf16 v[120:123], v[164:167], v[188:191], v[120:123]
	v_mfma_f32_16x16x32_bf16 v[124:127], v[152:155], v[202:205], v[124:127]
	v_mfma_f32_16x16x32_bf16 v[124:127], v[156:159], v[206:209], v[124:127]
	v_mfma_f32_16x16x32_bf16 v[128:131], v[160:163], v[202:205], v[128:131]
	v_mfma_f32_16x16x32_bf16 v[128:131], v[164:167], v[206:209], v[128:131]
	s_setprio 0
	s_barrier
	s_add_i32 s8, s72, 2
	s_add_u32 s52, s52, 0x100
	s_addc_u32 s53, s53, 0
	s_add_u32 s26, s26, 0x100
	s_addc_u32 s27, s27, 0
	s_cmp_ge_i32 s72, s82
	s_mov_b32 s72, s8
	s_cbranch_scc0 .LBB0_287

.LBB0_429:
	ds_read_b128 v[136:139], v2
	ds_read_b128 v[140:143], v2 offset:1024
	ds_read_b128 v[144:147], v2 offset:2048
	ds_read_b128 v[148:151], v2 offset:3072
	ds_read_b128 v[152:155], v132
	ds_read_b128 v[156:159], v132 offset:1024
	ds_read_b128 v[160:163], v132 offset:2048
	ds_read_b128 v[164:167], v132 offset:3072
	s_cmp_eq_u32 s73, s66
	s_cselect_b32 s17, s51, s49
	s_cselect_b32 s16, s50, s48
	s_cselect_b32 s21, s15, s27
	s_cselect_b32 s20, s14, s26
	s_add_u32 s18, s26, 0xffffff80
	s_addc_u32 s19, s27, -1
	s_mov_b32 m0, s40
	s_mov_b64 s[96:97], s[18:19]
	ds_read_b128 v[168:171], v199
	ds_read_b128 v[172:175], v199 offset:1024
	ds_read_b128 v[176:179], v199 offset:2048
	ds_read_b128 v[180:183], v199 offset:3072
	ds_read_b128 v[184:187], v199 offset:4096
	ds_read_b128 v[188:191], v199 offset:5120
	s_add_u32 s18, s18, s52
	global_load_lds_dwordx4 v194, s[96:97]
	s_mov_b32 m0, s41
	s_addc_u32 s19, s19, s53
	global_load_lds_dwordx4 v195, s[96:97]
	s_mov_b32 m0, s42
	ds_read_b128 v[202:205], v199 offset:6144
	global_load_lds_dwordx4 v194, s[18:19]
	s_mov_b32 m0, s43
	ds_read_b128 v[206:209], v199 offset:7168
	global_load_lds_dwordx4 v195, s[18:19]
	s_waitcnt vmcnt(8)
	s_waitcnt lgkmcnt(0)
	s_add_u32 s18, s16, 0x80
	s_addc_u32 s19, s17, 0
	s_barrier
	s_setprio 1
	s_waitcnt lgkmcnt(0)
	v_mfma_f32_16x16x32_bf16 v[4:7], v[136:139], v[168:171], v[4:7]
	v_mfma_f32_16x16x32_bf16 v[4:7], v[140:143], v[172:175], v[4:7]
	v_mfma_f32_16x16x32_bf16 v[8:11], v[144:147], v[168:171], v[8:11]
	v_mfma_f32_16x16x32_bf16 v[8:11], v[148:151], v[172:175], v[8:11]
	v_mfma_f32_16x16x32_bf16 v[12:15], v[136:139], v[176:179], v[12:15]
	v_mfma_f32_16x16x32_bf16 v[12:15], v[140:143], v[180:183], v[12:15]
	v_mfma_f32_16x16x32_bf16 v[16:19], v[144:147], v[176:179], v[16:19]
	v_mfma_f32_16x16x32_bf16 v[16:19], v[148:151], v[180:183], v[16:19]
	v_mfma_f32_16x16x32_bf16 v[20:23], v[136:139], v[184:187], v[20:23]
	v_mfma_f32_16x16x32_bf16 v[20:23], v[140:143], v[188:191], v[20:23]
	v_mfma_f32_16x16x32_bf16 v[24:27], v[144:147], v[184:187], v[24:27]
	v_mfma_f32_16x16x32_bf16 v[24:27], v[148:151], v[188:191], v[24:27]
	v_mfma_f32_16x16x32_bf16 v[28:31], v[136:139], v[202:205], v[28:31]
	v_mfma_f32_16x16x32_bf16 v[28:31], v[140:143], v[206:209], v[28:31]
	v_mfma_f32_16x16x32_bf16 v[32:35], v[144:147], v[202:205], v[32:35]
	v_mfma_f32_16x16x32_bf16 v[32:35], v[148:151], v[206:209], v[32:35]
	s_setprio 0
	s_setprio 1
	v_mfma_f32_16x16x32_bf16 v[36:39], v[152:155], v[168:171], v[36:39]
	v_mfma_f32_16x16x32_bf16 v[36:39], v[156:159], v[172:175], v[36:39]
	v_mfma_f32_16x16x32_bf16 v[40:43], v[160:163], v[168:171], v[40:43]
	v_mfma_f32_16x16x32_bf16 v[40:43], v[164:167], v[172:175], v[40:43]
	v_mfma_f32_16x16x32_bf16 v[44:47], v[152:155], v[176:179], v[44:47]
	v_mfma_f32_16x16x32_bf16 v[44:47], v[156:159], v[180:183], v[44:47]
	v_mfma_f32_16x16x32_bf16 v[48:51], v[160:163], v[176:179], v[48:51]
	v_mfma_f32_16x16x32_bf16 v[48:51], v[164:167], v[180:183], v[48:51]
	v_mfma_f32_16x16x32_bf16 v[52:55], v[152:155], v[184:187], v[52:55]
	v_mfma_f32_16x16x32_bf16 v[52:55], v[156:159], v[188:191], v[52:55]
	v_mfma_f32_16x16x32_bf16 v[56:59], v[160:163], v[184:187], v[56:59]
	v_mfma_f32_16x16x32_bf16 v[56:59], v[164:167], v[188:191], v[56:59]
	v_mfma_f32_16x16x32_bf16 v[60:63], v[152:155], v[202:205], v[60:63]
	v_mfma_f32_16x16x32_bf16 v[60:63], v[156:159], v[206:209], v[60:63]
	v_mfma_f32_16x16x32_bf16 v[64:67], v[160:163], v[202:205], v[64:67]
	v_mfma_f32_16x16x32_bf16 v[64:67], v[164:167], v[206:209], v[64:67]
	s_setprio 0
	s_barrier
	s_mov_b32 m0, s44
	s_mov_b64 s[96:97], s[16:17]
	ds_read_b128 v[168:171], v199 offset:16384
	ds_read_b128 v[172:175], v199 offset:17408
	ds_read_b128 v[176:179], v199 offset:18432
	ds_read_b128 v[180:183], v199 offset:19456
	ds_read_b128 v[184:187], v199 offset:20480
	ds_read_b128 v[188:191], v199 offset:21504
	s_add_u32 s16, s16, s52
	global_load_lds_dwordx4 v201, s[96:97]
	s_mov_b32 m0, s45
	s_addc_u32 s17, s17, s53
	global_load_lds_dwordx4 v200, s[96:97]
	s_mov_b32 m0, s30
	ds_read_b128 v[202:205], v199 offset:22528
	global_load_lds_dwordx4 v201, s[16:17]
	s_mov_b32 m0, s31
	ds_read_b128 v[206:209], v199 offset:23552
	global_load_lds_dwordx4 v200, s[16:17]
	s_waitcnt vmcnt(6)
	s_waitcnt lgkmcnt(0)
	s_barrier
	s_setprio 1
	s_waitcnt lgkmcnt(0)
	v_mfma_f32_16x16x32_bf16 v[68:71], v[136:139], v[168:171], v[68:71]
	v_mfma_f32_16x16x32_bf16 v[68:71], v[140:143], v[172:175], v[68:71]
	v_mfma_f32_16x16x32_bf16 v[72:75], v[144:147], v[168:171], v[72:75]
	v_mfma_f32_16x16x32_bf16 v[72:75], v[148:151], v[172:175], v[72:75]
	v_mfma_f32_16x16x32_bf16 v[76:79], v[136:139], v[176:179], v[76:79]
	v_mfma_f32_16x16x32_bf16 v[76:79], v[140:143], v[180:183], v[76:79]
	v_mfma_f32_16x16x32_bf16 v[80:83], v[144:147], v[176:179], v[80:83]
	v_mfma_f32_16x16x32_bf16 v[80:83], v[148:151], v[180:183], v[80:83]
	v_mfma_f32_16x16x32_bf16 v[84:87], v[136:139], v[184:187], v[84:87]
	v_mfma_f32_16x16x32_bf16 v[84:87], v[140:143], v[188:191], v[84:87]
	v_mfma_f32_16x16x32_bf16 v[88:91], v[144:147], v[184:187], v[88:91]
	v_mfma_f32_16x16x32_bf16 v[88:91], v[148:151], v[188:191], v[88:91]
	v_mfma_f32_16x16x32_bf16 v[92:95], v[136:139], v[202:205], v[92:95]
	v_mfma_f32_16x16x32_bf16 v[92:95], v[140:143], v[206:209], v[92:95]
	v_mfma_f32_16x16x32_bf16 v[96:99], v[144:147], v[202:205], v[96:99]
	v_mfma_f32_16x16x32_bf16 v[96:99], v[148:151], v[206:209], v[96:99]
	s_setprio 0
	s_setprio 1
	v_mfma_f32_16x16x32_bf16 v[100:103], v[152:155], v[168:171], v[100:103]
	v_mfma_f32_16x16x32_bf16 v[100:103], v[156:159], v[172:175], v[100:103]
	v_mfma_f32_16x16x32_bf16 v[104:107], v[160:163], v[168:171], v[104:107]
	v_mfma_f32_16x16x32_bf16 v[104:107], v[164:167], v[172:175], v[104:107]
	v_mfma_f32_16x16x32_bf16 v[108:111], v[152:155], v[176:179], v[108:111]
	v_mfma_f32_16x16x32_bf16 v[108:111], v[156:159], v[180:183], v[108:111]
	v_mfma_f32_16x16x32_bf16 v[112:115], v[160:163], v[176:179], v[112:115]
	v_mfma_f32_16x16x32_bf16 v[112:115], v[164:167], v[180:183], v[112:115]
	v_mfma_f32_16x16x32_bf16 v[116:119], v[152:155], v[184:187], v[116:119]
	v_mfma_f32_16x16x32_bf16 v[116:119], v[156:159], v[188:191], v[116:119]
	v_mfma_f32_16x16x32_bf16 v[120:123], v[160:163], v[184:187], v[120:123]
	v_mfma_f32_16x16x32_bf16 v[120:123], v[164:167], v[188:191], v[120:123]
	v_mfma_f32_16x16x32_bf16 v[124:127], v[152:155], v[202:205], v[124:127]
	v_mfma_f32_16x16x32_bf16 v[124:127], v[156:159], v[206:209], v[124:127]
	v_mfma_f32_16x16x32_bf16 v[128:131], v[160:163], v[202:205], v[128:131]
	v_mfma_f32_16x16x32_bf16 v[128:131], v[164:167], v[206:209], v[128:131]
	s_setprio 0
	s_barrier
	ds_read_b128 v[136:139], v133
	ds_read_b128 v[140:143], v133 offset:1024
	ds_read_b128 v[144:147], v133 offset:2048
	ds_read_b128 v[148:151], v133 offset:3072
	ds_read_b128 v[152:155], v134
	ds_read_b128 v[156:159], v134 offset:1024
	ds_read_b128 v[160:163], v134 offset:2048
	ds_read_b128 v[164:167], v134 offset:3072
	s_mov_b32 m0, s84
	s_mov_b64 s[16:17], s[20:21]
	ds_read_b128 v[168:171], v199 offset:32768
	ds_read_b128 v[172:175], v199 offset:33792
	ds_read_b128 v[176:179], v199 offset:34816
	ds_read_b128 v[180:183], v199 offset:35840
	ds_read_b128 v[184:187], v199 offset:36864
	global_load_lds_dwordx4 v194, s[16:17]
	s_mov_b32 m0, s85
	ds_read_b128 v[188:191], v199 offset:37888
	global_load_lds_dwordx4 v195, s[16:17]
	s_add_u32 s16, s20, s52
	s_addc_u32 s17, s21, s53
	s_mov_b32 m0, s86
	ds_read_b128 v[202:205], v199 offset:38912
	global_load_lds_dwordx4 v194, s[16:17]
	s_mov_b32 m0, s87
	ds_read_b128 v[206:209], v199 offset:39936
	global_load_lds_dwordx4 v195, s[16:17]
	s_waitcnt vmcnt(8)
	s_waitcnt lgkmcnt(0)
	s_barrier
	s_setprio 1
	s_waitcnt lgkmcnt(0)
	v_mfma_f32_16x16x32_bf16 v[4:7], v[136:139], v[168:171], v[4:7]
	v_mfma_f32_16x16x32_bf16 v[4:7], v[140:143], v[172:175], v[4:7]
	v_mfma_f32_16x16x32_bf16 v[8:11], v[144:147], v[168:171], v[8:11]
	v_mfma_f32_16x16x32_bf16 v[8:11], v[148:151], v[172:175], v[8:11]
	v_mfma_f32_16x16x32_bf16 v[12:15], v[136:139], v[176:179], v[12:15]
	v_mfma_f32_16x16x32_bf16 v[12:15], v[140:143], v[180:183], v[12:15]
	v_mfma_f32_16x16x32_bf16 v[16:19], v[144:147], v[176:179], v[16:19]
	v_mfma_f32_16x16x32_bf16 v[16:19], v[148:151], v[180:183], v[16:19]
	v_mfma_f32_16x16x32_bf16 v[20:23], v[136:139], v[184:187], v[20:23]
	v_mfma_f32_16x16x32_bf16 v[20:23], v[140:143], v[188:191], v[20:23]
	v_mfma_f32_16x16x32_bf16 v[24:27], v[144:147], v[184:187], v[24:27]
	v_mfma_f32_16x16x32_bf16 v[24:27], v[148:151], v[188:191], v[24:27]
	v_mfma_f32_16x16x32_bf16 v[28:31], v[136:139], v[202:205], v[28:31]
	v_mfma_f32_16x16x32_bf16 v[28:31], v[140:143], v[206:209], v[28:31]
	v_mfma_f32_16x16x32_bf16 v[32:35], v[144:147], v[202:205], v[32:35]
	v_mfma_f32_16x16x32_bf16 v[32:35], v[148:151], v[206:209], v[32:35]
	s_setprio 0
	s_setprio 1
	v_mfma_f32_16x16x32_bf16 v[36:39], v[152:155], v[168:171], v[36:39]
	v_mfma_f32_16x16x32_bf16 v[36:39], v[156:159], v[172:175], v[36:39]
	v_mfma_f32_16x16x32_bf16 v[40:43], v[160:163], v[168:171], v[40:43]
	v_mfma_f32_16x16x32_bf16 v[40:43], v[164:167], v[172:175], v[40:43]
	v_mfma_f32_16x16x32_bf16 v[44:47], v[152:155], v[176:179], v[44:47]
	v_mfma_f32_16x16x32_bf16 v[44:47], v[156:159], v[180:183], v[44:47]
	v_mfma_f32_16x16x32_bf16 v[48:51], v[160:163], v[176:179], v[48:51]
	v_mfma_f32_16x16x32_bf16 v[48:51], v[164:167], v[180:183], v[48:51]
	v_mfma_f32_16x16x32_bf16 v[52:55], v[152:155], v[184:187], v[52:55]
	v_mfma_f32_16x16x32_bf16 v[52:55], v[156:159], v[188:191], v[52:55]
	v_mfma_f32_16x16x32_bf16 v[56:59], v[160:163], v[184:187], v[56:59]
	v_mfma_f32_16x16x32_bf16 v[56:59], v[164:167], v[188:191], v[56:59]
	v_mfma_f32_16x16x32_bf16 v[60:63], v[152:155], v[202:205], v[60:63]
	v_mfma_f32_16x16x32_bf16 v[60:63], v[156:159], v[206:209], v[60:63]
	v_mfma_f32_16x16x32_bf16 v[64:67], v[160:163], v[202:205], v[64:67]
	v_mfma_f32_16x16x32_bf16 v[64:67], v[164:167], v[206:209], v[64:67]
	s_setprio 0
	s_barrier
	s_mov_b32 m0, s46
	s_mov_b64 s[16:17], s[18:19]
	ds_read_b128 v[168:171], v199 offset:49152
	ds_read_b128 v[172:175], v199 offset:50176
	ds_read_b128 v[176:179], v199 offset:51200
	ds_read_b128 v[180:183], v199 offset:52224
	ds_read_b128 v[184:187], v199 offset:53248
	global_load_lds_dwordx4 v201, s[16:17]
	s_mov_b32 m0, s47
	ds_read_b128 v[188:191], v199 offset:54272
	global_load_lds_dwordx4 v200, s[16:17]
	s_add_u32 s16, s18, s52
	s_addc_u32 s17, s19, s53
	s_mov_b32 m0, s28
	ds_read_b128 v[202:205], v199 offset:55296
	global_load_lds_dwordx4 v201, s[16:17]
	s_mov_b32 m0, s29
	ds_read_b128 v[206:209], v199 offset:56320
	global_load_lds_dwordx4 v200, s[16:17]
	s_waitcnt vmcnt(6)
	s_waitcnt lgkmcnt(0)
	s_barrier
	s_setprio 1
	s_waitcnt lgkmcnt(0)
	v_mfma_f32_16x16x32_bf16 v[68:71], v[136:139], v[168:171], v[68:71]
	v_mfma_f32_16x16x32_bf16 v[68:71], v[140:143], v[172:175], v[68:71]
	v_mfma_f32_16x16x32_bf16 v[72:75], v[144:147], v[168:171], v[72:75]
	v_mfma_f32_16x16x32_bf16 v[72:75], v[148:151], v[172:175], v[72:75]
	v_mfma_f32_16x16x32_bf16 v[76:79], v[136:139], v[176:179], v[76:79]
	v_mfma_f32_16x16x32_bf16 v[76:79], v[140:143], v[180:183], v[76:79]
	v_mfma_f32_16x16x32_bf16 v[80:83], v[144:147], v[176:179], v[80:83]
	v_mfma_f32_16x16x32_bf16 v[80:83], v[148:151], v[180:183], v[80:83]
	v_mfma_f32_16x16x32_bf16 v[84:87], v[136:139], v[184:187], v[84:87]
	v_mfma_f32_16x16x32_bf16 v[84:87], v[140:143], v[188:191], v[84:87]
	v_mfma_f32_16x16x32_bf16 v[88:91], v[144:147], v[184:187], v[88:91]
	v_mfma_f32_16x16x32_bf16 v[88:91], v[148:151], v[188:191], v[88:91]
	v_mfma_f32_16x16x32_bf16 v[92:95], v[136:139], v[202:205], v[92:95]
	v_mfma_f32_16x16x32_bf16 v[92:95], v[140:143], v[206:209], v[92:95]
	v_mfma_f32_16x16x32_bf16 v[96:99], v[144:147], v[202:205], v[96:99]
	v_mfma_f32_16x16x32_bf16 v[96:99], v[148:151], v[206:209], v[96:99]
	s_setprio 0
	s_setprio 1
	v_mfma_f32_16x16x32_bf16 v[100:103], v[152:155], v[168:171], v[100:103]
	v_mfma_f32_16x16x32_bf16 v[100:103], v[156:159], v[172:175], v[100:103]
	v_mfma_f32_16x16x32_bf16 v[104:107], v[160:163], v[168:171], v[104:107]
	v_mfma_f32_16x16x32_bf16 v[104:107], v[164:167], v[172:175], v[104:107]
	v_mfma_f32_16x16x32_bf16 v[108:111], v[152:155], v[176:179], v[108:111]
	v_mfma_f32_16x16x32_bf16 v[108:111], v[156:159], v[180:183], v[108:111]
	v_mfma_f32_16x16x32_bf16 v[112:115], v[160:163], v[176:179], v[112:115]
	v_mfma_f32_16x16x32_bf16 v[112:115], v[164:167], v[180:183], v[112:115]
	v_mfma_f32_16x16x32_bf16 v[116:119], v[152:155], v[184:187], v[116:119]
	v_mfma_f32_16x16x32_bf16 v[116:119], v[156:159], v[188:191], v[116:119]
	v_mfma_f32_16x16x32_bf16 v[120:123], v[160:163], v[184:187], v[120:123]
	v_mfma_f32_16x16x32_bf16 v[120:123], v[164:167], v[188:191], v[120:123]
	v_mfma_f32_16x16x32_bf16 v[124:127], v[152:155], v[202:205], v[124:127]
	v_mfma_f32_16x16x32_bf16 v[124:127], v[156:159], v[206:209], v[124:127]
	v_mfma_f32_16x16x32_bf16 v[128:131], v[160:163], v[202:205], v[128:131]
	v_mfma_f32_16x16x32_bf16 v[128:131], v[164:167], v[206:209], v[128:131]
	s_setprio 0
	s_barrier
	s_add_i32 s8, s66, 2
	s_add_u32 s48, s48, 0x100
	s_addc_u32 s49, s49, 0
	s_add_u32 s26, s26, 0x100
	s_addc_u32 s27, s27, 0
	s_cmp_ge_i32 s66, s73
	s_mov_b32 s66, s8
	s_cbranch_scc0 .LBB0_429
	v_readlane_b32 s96, v255, 41
	v_readlane_b32 s97, v255, 42

.LBB0_855:
	ds_read_b128 v[136:139], v132
	ds_read_b128 v[140:143], v132 offset:1024
	ds_read_b128 v[144:147], v132 offset:2048
	ds_read_b128 v[148:151], v132 offset:3072
	ds_read_b128 v[152:155], v133
	ds_read_b128 v[156:159], v133 offset:1024
	ds_read_b128 v[160:163], v133 offset:2048
	ds_read_b128 v[164:167], v133 offset:3072
	s_cmp_eq_u32 s4, s90
	s_cselect_b32 s17, s41, s89
	s_cselect_b32 s16, s40, s88
	s_cselect_b32 s21, s59, s27
	s_cselect_b32 s20, s58, s26
	s_add_u32 s8, s26, 0xffffff80
	s_addc_u32 s9, s27, -1
	s_mov_b32 m0, s80
	s_mov_b64 s[18:19], s[8:9]
	ds_read_b128 v[168:171], v246 offset:8192
	ds_read_b128 v[172:175], v246 offset:9216
	ds_read_b128 v[176:179], v246 offset:10240
	ds_read_b128 v[180:183], v246 offset:11264
	ds_read_b128 v[184:187], v246 offset:12288
	ds_read_b128 v[188:191], v246 offset:13312
	ds_read_b128 v[192:195], v246 offset:14336
	ds_read_b128 v[196:199], v246 offset:15360
	s_add_u32 s8, s8, s42
	global_load_lds_dwordx4 v242, s[18:19]
	s_mov_b32 m0, s81
	s_addc_u32 s9, s9, s43
	global_load_lds_dwordx4 v2, s[18:19]
	s_mov_b32 m0, s82
	s_add_u32 s18, s16, 0x80
	global_load_lds_dwordx4 v242, s[8:9]
	s_mov_b32 m0, s83
	s_addc_u32 s19, s17, 0
	global_load_lds_dwordx4 v2, s[8:9]
	s_waitcnt vmcnt(8)
	s_waitcnt lgkmcnt(0)
	s_barrier
	s_setprio 1
	s_waitcnt lgkmcnt(0)
	v_mfma_f32_16x16x32_bf16 v[4:7], v[136:139], v[168:171], v[4:7]
	v_mfma_f32_16x16x32_bf16 v[4:7], v[140:143], v[172:175], v[4:7]
	v_mfma_f32_16x16x32_bf16 v[8:11], v[144:147], v[168:171], v[8:11]
	v_mfma_f32_16x16x32_bf16 v[8:11], v[148:151], v[172:175], v[8:11]
	v_mfma_f32_16x16x32_bf16 v[12:15], v[136:139], v[176:179], v[12:15]
	v_mfma_f32_16x16x32_bf16 v[12:15], v[140:143], v[180:183], v[12:15]
	v_mfma_f32_16x16x32_bf16 v[16:19], v[144:147], v[176:179], v[16:19]
	v_mfma_f32_16x16x32_bf16 v[16:19], v[148:151], v[180:183], v[16:19]
	v_mfma_f32_16x16x32_bf16 v[20:23], v[136:139], v[184:187], v[20:23]
	v_mfma_f32_16x16x32_bf16 v[20:23], v[140:143], v[188:191], v[20:23]
	v_mfma_f32_16x16x32_bf16 v[24:27], v[144:147], v[184:187], v[24:27]
	v_mfma_f32_16x16x32_bf16 v[24:27], v[148:151], v[188:191], v[24:27]
	v_mfma_f32_16x16x32_bf16 v[28:31], v[136:139], v[192:195], v[28:31]
	v_mfma_f32_16x16x32_bf16 v[28:31], v[140:143], v[196:199], v[28:31]
	v_mfma_f32_16x16x32_bf16 v[32:35], v[144:147], v[192:195], v[32:35]
	v_mfma_f32_16x16x32_bf16 v[32:35], v[148:151], v[196:199], v[32:35]
	s_setprio 0
	s_setprio 1
	v_mfma_f32_16x16x32_bf16 v[36:39], v[152:155], v[168:171], v[36:39]
	v_mfma_f32_16x16x32_bf16 v[36:39], v[156:159], v[172:175], v[36:39]
	v_mfma_f32_16x16x32_bf16 v[40:43], v[160:163], v[168:171], v[40:43]
	v_mfma_f32_16x16x32_bf16 v[40:43], v[164:167], v[172:175], v[40:43]
	v_mfma_f32_16x16x32_bf16 v[44:47], v[152:155], v[176:179], v[44:47]
	v_mfma_f32_16x16x32_bf16 v[44:47], v[156:159], v[180:183], v[44:47]
	v_mfma_f32_16x16x32_bf16 v[48:51], v[160:163], v[176:179], v[48:51]
	v_mfma_f32_16x16x32_bf16 v[48:51], v[164:167], v[180:183], v[48:51]
	v_mfma_f32_16x16x32_bf16 v[52:55], v[152:155], v[184:187], v[52:55]
	v_mfma_f32_16x16x32_bf16 v[52:55], v[156:159], v[188:191], v[52:55]
	v_mfma_f32_16x16x32_bf16 v[56:59], v[160:163], v[184:187], v[56:59]
	v_mfma_f32_16x16x32_bf16 v[56:59], v[164:167], v[188:191], v[56:59]
	v_mfma_f32_16x16x32_bf16 v[60:63], v[152:155], v[192:195], v[60:63]
	v_mfma_f32_16x16x32_bf16 v[60:63], v[156:159], v[196:199], v[60:63]
	v_mfma_f32_16x16x32_bf16 v[64:67], v[160:163], v[192:195], v[64:67]
	v_mfma_f32_16x16x32_bf16 v[64:67], v[164:167], v[196:199], v[64:67]
	s_setprio 0
	s_barrier
	s_mov_b32 m0, s84
	s_mov_b64 s[8:9], s[16:17]
	ds_read_b128 v[168:171], v246 offset:24576
	ds_read_b128 v[172:175], v246 offset:25600
	ds_read_b128 v[176:179], v246 offset:26624
	ds_read_b128 v[180:183], v246 offset:27648
	ds_read_b128 v[184:187], v246 offset:28672
	global_load_lds_dwordx4 v248, s[8:9]
	s_mov_b32 m0, s85
	ds_read_b128 v[188:191], v246 offset:29696
	global_load_lds_dwordx4 v247, s[8:9]
	s_add_u32 s8, s16, s42
	s_addc_u32 s9, s17, s43
	s_mov_b32 m0, s30
	ds_read_b128 v[192:195], v246 offset:30720
	global_load_lds_dwordx4 v248, s[8:9]
	s_mov_b32 m0, s31
	ds_read_b128 v[196:199], v246 offset:31744
	global_load_lds_dwordx4 v247, s[8:9]
	s_waitcnt vmcnt(6)
	s_waitcnt lgkmcnt(0)
	s_barrier
	s_setprio 1
	s_waitcnt lgkmcnt(0)
	v_mfma_f32_16x16x32_bf16 v[68:71], v[136:139], v[168:171], v[68:71]
	v_mfma_f32_16x16x32_bf16 v[68:71], v[140:143], v[172:175], v[68:71]
	v_mfma_f32_16x16x32_bf16 v[72:75], v[144:147], v[168:171], v[72:75]
	v_mfma_f32_16x16x32_bf16 v[72:75], v[148:151], v[172:175], v[72:75]
	v_mfma_f32_16x16x32_bf16 v[76:79], v[136:139], v[176:179], v[76:79]
	v_mfma_f32_16x16x32_bf16 v[76:79], v[140:143], v[180:183], v[76:79]
	v_mfma_f32_16x16x32_bf16 v[80:83], v[144:147], v[176:179], v[80:83]
	v_mfma_f32_16x16x32_bf16 v[80:83], v[148:151], v[180:183], v[80:83]
	v_mfma_f32_16x16x32_bf16 v[84:87], v[136:139], v[184:187], v[84:87]
	v_mfma_f32_16x16x32_bf16 v[84:87], v[140:143], v[188:191], v[84:87]
	v_mfma_f32_16x16x32_bf16 v[88:91], v[144:147], v[184:187], v[88:91]
	v_mfma_f32_16x16x32_bf16 v[88:91], v[148:151], v[188:191], v[88:91]
	v_mfma_f32_16x16x32_bf16 v[92:95], v[136:139], v[192:195], v[92:95]
	v_mfma_f32_16x16x32_bf16 v[92:95], v[140:143], v[196:199], v[92:95]
	v_mfma_f32_16x16x32_bf16 v[96:99], v[144:147], v[192:195], v[96:99]
	v_mfma_f32_16x16x32_bf16 v[96:99], v[148:151], v[196:199], v[96:99]
	s_setprio 0
	s_setprio 1
	v_mfma_f32_16x16x32_bf16 v[100:103], v[152:155], v[168:171], v[100:103]
	v_mfma_f32_16x16x32_bf16 v[100:103], v[156:159], v[172:175], v[100:103]
	v_mfma_f32_16x16x32_bf16 v[104:107], v[160:163], v[168:171], v[104:107]
	v_mfma_f32_16x16x32_bf16 v[104:107], v[164:167], v[172:175], v[104:107]
	v_mfma_f32_16x16x32_bf16 v[108:111], v[152:155], v[176:179], v[108:111]
	v_mfma_f32_16x16x32_bf16 v[108:111], v[156:159], v[180:183], v[108:111]
	v_mfma_f32_16x16x32_bf16 v[112:115], v[160:163], v[176:179], v[112:115]
	v_mfma_f32_16x16x32_bf16 v[112:115], v[164:167], v[180:183], v[112:115]
	v_mfma_f32_16x16x32_bf16 v[116:119], v[152:155], v[184:187], v[116:119]
	v_mfma_f32_16x16x32_bf16 v[116:119], v[156:159], v[188:191], v[116:119]
	v_mfma_f32_16x16x32_bf16 v[120:123], v[160:163], v[184:187], v[120:123]
	v_mfma_f32_16x16x32_bf16 v[120:123], v[164:167], v[188:191], v[120:123]
	v_mfma_f32_16x16x32_bf16 v[124:127], v[152:155], v[192:195], v[124:127]
	v_mfma_f32_16x16x32_bf16 v[124:127], v[156:159], v[196:199], v[124:127]
	v_mfma_f32_16x16x32_bf16 v[128:131], v[160:163], v[192:195], v[128:131]
	v_mfma_f32_16x16x32_bf16 v[128:131], v[164:167], v[196:199], v[128:131]
	s_setprio 0
	s_barrier
	ds_read_b128 v[136:139], v134
	ds_read_b128 v[140:143], v134 offset:1024
	ds_read_b128 v[144:147], v134 offset:2048
	ds_read_b128 v[148:151], v134 offset:3072
	ds_read_b128 v[152:155], v135
	ds_read_b128 v[156:159], v135 offset:1024
	ds_read_b128 v[160:163], v135 offset:2048
	ds_read_b128 v[164:167], v135 offset:3072
	s_mov_b32 m0, s7
	s_mov_b64 s[8:9], s[20:21]
	ds_read_b128 v[168:171], v246 offset:40960
	ds_read_b128 v[172:175], v246 offset:41984
	ds_read_b128 v[176:179], v246 offset:43008
	ds_read_b128 v[180:183], v246 offset:44032
	ds_read_b128 v[184:187], v246 offset:45056
	global_load_lds_dwordx4 v242, s[8:9]
	s_mov_b32 m0, s69
	ds_read_b128 v[188:191], v246 offset:46080
	global_load_lds_dwordx4 v2, s[8:9]
	s_add_u32 s8, s20, s42
	s_addc_u32 s9, s21, s43
	s_mov_b32 m0, s72
	ds_read_b128 v[192:195], v246 offset:47104
	global_load_lds_dwordx4 v242, s[8:9]
	s_mov_b32 m0, s73
	ds_read_b128 v[196:199], v246 offset:48128
	global_load_lds_dwordx4 v2, s[8:9]
	s_waitcnt vmcnt(8)
	s_waitcnt lgkmcnt(0)
	s_barrier
	s_setprio 1
	s_waitcnt lgkmcnt(0)
	v_mfma_f32_16x16x32_bf16 v[4:7], v[136:139], v[168:171], v[4:7]
	v_mfma_f32_16x16x32_bf16 v[4:7], v[140:143], v[172:175], v[4:7]
	v_mfma_f32_16x16x32_bf16 v[8:11], v[144:147], v[168:171], v[8:11]
	v_mfma_f32_16x16x32_bf16 v[8:11], v[148:151], v[172:175], v[8:11]
	v_mfma_f32_16x16x32_bf16 v[12:15], v[136:139], v[176:179], v[12:15]
	v_mfma_f32_16x16x32_bf16 v[12:15], v[140:143], v[180:183], v[12:15]
	v_mfma_f32_16x16x32_bf16 v[16:19], v[144:147], v[176:179], v[16:19]
	v_mfma_f32_16x16x32_bf16 v[16:19], v[148:151], v[180:183], v[16:19]
	v_mfma_f32_16x16x32_bf16 v[20:23], v[136:139], v[184:187], v[20:23]
	v_mfma_f32_16x16x32_bf16 v[20:23], v[140:143], v[188:191], v[20:23]
	v_mfma_f32_16x16x32_bf16 v[24:27], v[144:147], v[184:187], v[24:27]
	v_mfma_f32_16x16x32_bf16 v[24:27], v[148:151], v[188:191], v[24:27]
	v_mfma_f32_16x16x32_bf16 v[28:31], v[136:139], v[192:195], v[28:31]
	v_mfma_f32_16x16x32_bf16 v[28:31], v[140:143], v[196:199], v[28:31]
	v_mfma_f32_16x16x32_bf16 v[32:35], v[144:147], v[192:195], v[32:35]
	v_mfma_f32_16x16x32_bf16 v[32:35], v[148:151], v[196:199], v[32:35]
	s_setprio 0
	s_setprio 1
	v_mfma_f32_16x16x32_bf16 v[36:39], v[152:155], v[168:171], v[36:39]
	v_mfma_f32_16x16x32_bf16 v[36:39], v[156:159], v[172:175], v[36:39]
	v_mfma_f32_16x16x32_bf16 v[40:43], v[160:163], v[168:171], v[40:43]
	v_mfma_f32_16x16x32_bf16 v[40:43], v[164:167], v[172:175], v[40:43]
	v_mfma_f32_16x16x32_bf16 v[44:47], v[152:155], v[176:179], v[44:47]
	v_mfma_f32_16x16x32_bf16 v[44:47], v[156:159], v[180:183], v[44:47]
	v_mfma_f32_16x16x32_bf16 v[48:51], v[160:163], v[176:179], v[48:51]
	v_mfma_f32_16x16x32_bf16 v[48:51], v[164:167], v[180:183], v[48:51]
	v_mfma_f32_16x16x32_bf16 v[52:55], v[152:155], v[184:187], v[52:55]
	v_mfma_f32_16x16x32_bf16 v[52:55], v[156:159], v[188:191], v[52:55]
	v_mfma_f32_16x16x32_bf16 v[56:59], v[160:163], v[184:187], v[56:59]
	v_mfma_f32_16x16x32_bf16 v[56:59], v[164:167], v[188:191], v[56:59]
	v_mfma_f32_16x16x32_bf16 v[60:63], v[152:155], v[192:195], v[60:63]
	v_mfma_f32_16x16x32_bf16 v[60:63], v[156:159], v[196:199], v[60:63]
	v_mfma_f32_16x16x32_bf16 v[64:67], v[160:163], v[192:195], v[64:67]
	v_mfma_f32_16x16x32_bf16 v[64:67], v[164:167], v[196:199], v[64:67]
	s_setprio 0
	s_barrier
	s_mov_b32 m0, s86
	s_mov_b64 s[8:9], s[18:19]
	ds_read_b128 v[168:171], v246 offset:57344
	ds_read_b128 v[172:175], v246 offset:58368
	ds_read_b128 v[176:179], v246 offset:59392
	ds_read_b128 v[180:183], v246 offset:60416
	ds_read_b128 v[184:187], v246 offset:61440
	global_load_lds_dwordx4 v248, s[8:9]
	s_mov_b32 m0, s87
	ds_read_b128 v[188:191], v246 offset:62464
	global_load_lds_dwordx4 v247, s[8:9]
	s_add_u32 s8, s18, s42
	s_addc_u32 s9, s19, s43
	s_mov_b32 m0, s28
	ds_read_b128 v[192:195], v246 offset:63488
	global_load_lds_dwordx4 v248, s[8:9]
	s_mov_b32 m0, s29
	ds_read_b128 v[196:199], v246 offset:64512
	global_load_lds_dwordx4 v247, s[8:9]
	s_waitcnt vmcnt(6)
	s_waitcnt lgkmcnt(0)
	s_barrier
	s_setprio 1
	s_waitcnt lgkmcnt(0)
	v_mfma_f32_16x16x32_bf16 v[68:71], v[136:139], v[168:171], v[68:71]
	v_mfma_f32_16x16x32_bf16 v[68:71], v[140:143], v[172:175], v[68:71]
	v_mfma_f32_16x16x32_bf16 v[72:75], v[144:147], v[168:171], v[72:75]
	v_mfma_f32_16x16x32_bf16 v[72:75], v[148:151], v[172:175], v[72:75]
	v_mfma_f32_16x16x32_bf16 v[76:79], v[136:139], v[176:179], v[76:79]
	v_mfma_f32_16x16x32_bf16 v[76:79], v[140:143], v[180:183], v[76:79]
	v_mfma_f32_16x16x32_bf16 v[80:83], v[144:147], v[176:179], v[80:83]
	v_mfma_f32_16x16x32_bf16 v[80:83], v[148:151], v[180:183], v[80:83]
	v_mfma_f32_16x16x32_bf16 v[84:87], v[136:139], v[184:187], v[84:87]
	v_mfma_f32_16x16x32_bf16 v[84:87], v[140:143], v[188:191], v[84:87]
	v_mfma_f32_16x16x32_bf16 v[88:91], v[144:147], v[184:187], v[88:91]
	v_mfma_f32_16x16x32_bf16 v[88:91], v[148:151], v[188:191], v[88:91]
	v_mfma_f32_16x16x32_bf16 v[92:95], v[136:139], v[192:195], v[92:95]
	v_mfma_f32_16x16x32_bf16 v[92:95], v[140:143], v[196:199], v[92:95]
	v_mfma_f32_16x16x32_bf16 v[96:99], v[144:147], v[192:195], v[96:99]
	v_mfma_f32_16x16x32_bf16 v[96:99], v[148:151], v[196:199], v[96:99]
	s_setprio 0
	s_setprio 1
	v_mfma_f32_16x16x32_bf16 v[100:103], v[152:155], v[168:171], v[100:103]
	v_mfma_f32_16x16x32_bf16 v[100:103], v[156:159], v[172:175], v[100:103]
	v_mfma_f32_16x16x32_bf16 v[104:107], v[160:163], v[168:171], v[104:107]
	v_mfma_f32_16x16x32_bf16 v[104:107], v[164:167], v[172:175], v[104:107]
	v_mfma_f32_16x16x32_bf16 v[108:111], v[152:155], v[176:179], v[108:111]
	v_mfma_f32_16x16x32_bf16 v[108:111], v[156:159], v[180:183], v[108:111]
	v_mfma_f32_16x16x32_bf16 v[112:115], v[160:163], v[176:179], v[112:115]
	v_mfma_f32_16x16x32_bf16 v[112:115], v[164:167], v[180:183], v[112:115]
	v_mfma_f32_16x16x32_bf16 v[116:119], v[152:155], v[184:187], v[116:119]
	v_mfma_f32_16x16x32_bf16 v[116:119], v[156:159], v[188:191], v[116:119]
	v_mfma_f32_16x16x32_bf16 v[120:123], v[160:163], v[184:187], v[120:123]
	v_mfma_f32_16x16x32_bf16 v[120:123], v[164:167], v[188:191], v[120:123]
	v_mfma_f32_16x16x32_bf16 v[124:127], v[152:155], v[192:195], v[124:127]
	v_mfma_f32_16x16x32_bf16 v[124:127], v[156:159], v[196:199], v[124:127]
	v_mfma_f32_16x16x32_bf16 v[128:131], v[160:163], v[192:195], v[128:131]
	v_mfma_f32_16x16x32_bf16 v[128:131], v[164:167], v[196:199], v[128:131]
	s_setprio 0
	s_barrier
	s_add_i32 s8, s90, 2
	s_add_u32 s88, s88, 0x100
	s_addc_u32 s89, s89, 0
	s_add_u32 s26, s26, 0x100
	s_addc_u32 s27, s27, 0
	s_cmp_ge_i32 s90, s4
	s_mov_b32 s90, s8
	s_cbranch_scc0 .LBB0_855
	v_readlane_b32 s90, v255, 45
	v_readlane_b32 s91, v255, 46
	s_movk_i32 s89, 0x61

.LBB0_880:
	ds_read_b128 v[136:139], v132
	ds_read_b128 v[140:143], v132 offset:1024
	ds_read_b128 v[144:147], v132 offset:2048
	ds_read_b128 v[148:151], v132 offset:3072
	ds_read_b128 v[152:155], v133
	ds_read_b128 v[156:159], v133 offset:1024
	ds_read_b128 v[160:163], v133 offset:2048
	ds_read_b128 v[164:167], v133 offset:3072
	s_cmp_eq_u32 s4, s88
	s_cselect_b32 s17, s43, s87
	s_cselect_b32 s16, s42, s86
	s_cselect_b32 s21, s41, s27
	s_cselect_b32 s20, s40, s26
	s_add_u32 s8, s26, 0xffffff80
	s_addc_u32 s9, s27, -1
	s_mov_b32 m0, s78
	s_mov_b64 s[18:19], s[8:9]
	ds_read_b128 v[168:171], v246
	ds_read_b128 v[172:175], v246 offset:1024
	ds_read_b128 v[176:179], v246 offset:2048
	ds_read_b128 v[180:183], v246 offset:3072
	ds_read_b128 v[184:187], v246 offset:4096
	ds_read_b128 v[188:191], v246 offset:5120
	ds_read_b128 v[192:195], v246 offset:6144
	ds_read_b128 v[196:199], v246 offset:7168
	s_add_u32 s8, s8, s46
	global_load_lds_dwordx4 v242, s[18:19]
	s_mov_b32 m0, s79
	s_addc_u32 s9, s9, s47
	global_load_lds_dwordx4 v2, s[18:19]
	s_mov_b32 m0, s80
	s_add_u32 s18, s16, 0x80
	global_load_lds_dwordx4 v242, s[8:9]
	s_mov_b32 m0, s81
	s_addc_u32 s19, s17, 0
	global_load_lds_dwordx4 v2, s[8:9]
	s_waitcnt vmcnt(8)
	s_waitcnt lgkmcnt(0)
	s_barrier
	s_setprio 1
	s_waitcnt lgkmcnt(0)
	v_mfma_f32_16x16x32_bf16 v[4:7], v[136:139], v[168:171], v[4:7]
	v_mfma_f32_16x16x32_bf16 v[4:7], v[140:143], v[172:175], v[4:7]
	v_mfma_f32_16x16x32_bf16 v[8:11], v[144:147], v[168:171], v[8:11]
	v_mfma_f32_16x16x32_bf16 v[8:11], v[148:151], v[172:175], v[8:11]
	v_mfma_f32_16x16x32_bf16 v[12:15], v[136:139], v[176:179], v[12:15]
	v_mfma_f32_16x16x32_bf16 v[12:15], v[140:143], v[180:183], v[12:15]
	v_mfma_f32_16x16x32_bf16 v[16:19], v[144:147], v[176:179], v[16:19]
	v_mfma_f32_16x16x32_bf16 v[16:19], v[148:151], v[180:183], v[16:19]
	v_mfma_f32_16x16x32_bf16 v[20:23], v[136:139], v[184:187], v[20:23]
	v_mfma_f32_16x16x32_bf16 v[20:23], v[140:143], v[188:191], v[20:23]
	v_mfma_f32_16x16x32_bf16 v[24:27], v[144:147], v[184:187], v[24:27]
	v_mfma_f32_16x16x32_bf16 v[24:27], v[148:151], v[188:191], v[24:27]
	v_mfma_f32_16x16x32_bf16 v[28:31], v[136:139], v[192:195], v[28:31]
	v_mfma_f32_16x16x32_bf16 v[28:31], v[140:143], v[196:199], v[28:31]
	v_mfma_f32_16x16x32_bf16 v[32:35], v[144:147], v[192:195], v[32:35]
	v_mfma_f32_16x16x32_bf16 v[32:35], v[148:151], v[196:199], v[32:35]
	s_setprio 0
	s_setprio 1
	v_mfma_f32_16x16x32_bf16 v[36:39], v[152:155], v[168:171], v[36:39]
	v_mfma_f32_16x16x32_bf16 v[36:39], v[156:159], v[172:175], v[36:39]
	v_mfma_f32_16x16x32_bf16 v[40:43], v[160:163], v[168:171], v[40:43]
	v_mfma_f32_16x16x32_bf16 v[40:43], v[164:167], v[172:175], v[40:43]
	v_mfma_f32_16x16x32_bf16 v[44:47], v[152:155], v[176:179], v[44:47]
	v_mfma_f32_16x16x32_bf16 v[44:47], v[156:159], v[180:183], v[44:47]
	v_mfma_f32_16x16x32_bf16 v[48:51], v[160:163], v[176:179], v[48:51]
	v_mfma_f32_16x16x32_bf16 v[48:51], v[164:167], v[180:183], v[48:51]
	v_mfma_f32_16x16x32_bf16 v[52:55], v[152:155], v[184:187], v[52:55]
	v_mfma_f32_16x16x32_bf16 v[52:55], v[156:159], v[188:191], v[52:55]
	v_mfma_f32_16x16x32_bf16 v[56:59], v[160:163], v[184:187], v[56:59]
	v_mfma_f32_16x16x32_bf16 v[56:59], v[164:167], v[188:191], v[56:59]
	v_mfma_f32_16x16x32_bf16 v[60:63], v[152:155], v[192:195], v[60:63]
	v_mfma_f32_16x16x32_bf16 v[60:63], v[156:159], v[196:199], v[60:63]
	v_mfma_f32_16x16x32_bf16 v[64:67], v[160:163], v[192:195], v[64:67]
	v_mfma_f32_16x16x32_bf16 v[64:67], v[164:167], v[196:199], v[64:67]
	s_setprio 0
	s_barrier
	s_mov_b32 m0, s82
	s_mov_b64 s[8:9], s[16:17]
	ds_read_b128 v[168:171], v246 offset:16384
	ds_read_b128 v[172:175], v246 offset:17408
	ds_read_b128 v[176:179], v246 offset:18432
	ds_read_b128 v[180:183], v246 offset:19456
	ds_read_b128 v[184:187], v246 offset:20480
	global_load_lds_dwordx4 v248, s[8:9]
	s_mov_b32 m0, s83
	ds_read_b128 v[188:191], v246 offset:21504
	global_load_lds_dwordx4 v247, s[8:9]
	s_add_u32 s8, s16, s46
	s_addc_u32 s9, s17, s47
	s_mov_b32 m0, s30
	ds_read_b128 v[192:195], v246 offset:22528
	global_load_lds_dwordx4 v248, s[8:9]
	s_mov_b32 m0, s31
	ds_read_b128 v[196:199], v246 offset:23552
	global_load_lds_dwordx4 v247, s[8:9]
	s_waitcnt vmcnt(6)
	s_waitcnt lgkmcnt(0)
	s_barrier
	s_setprio 1
	s_waitcnt lgkmcnt(0)
	v_mfma_f32_16x16x32_bf16 v[68:71], v[136:139], v[168:171], v[68:71]
	v_mfma_f32_16x16x32_bf16 v[68:71], v[140:143], v[172:175], v[68:71]
	v_mfma_f32_16x16x32_bf16 v[72:75], v[144:147], v[168:171], v[72:75]
	v_mfma_f32_16x16x32_bf16 v[72:75], v[148:151], v[172:175], v[72:75]
	v_mfma_f32_16x16x32_bf16 v[76:79], v[136:139], v[176:179], v[76:79]
	v_mfma_f32_16x16x32_bf16 v[76:79], v[140:143], v[180:183], v[76:79]
	v_mfma_f32_16x16x32_bf16 v[80:83], v[144:147], v[176:179], v[80:83]
	v_mfma_f32_16x16x32_bf16 v[80:83], v[148:151], v[180:183], v[80:83]
	v_mfma_f32_16x16x32_bf16 v[84:87], v[136:139], v[184:187], v[84:87]
	v_mfma_f32_16x16x32_bf16 v[84:87], v[140:143], v[188:191], v[84:87]
	v_mfma_f32_16x16x32_bf16 v[88:91], v[144:147], v[184:187], v[88:91]
	v_mfma_f32_16x16x32_bf16 v[88:91], v[148:151], v[188:191], v[88:91]
	v_mfma_f32_16x16x32_bf16 v[92:95], v[136:139], v[192:195], v[92:95]
	v_mfma_f32_16x16x32_bf16 v[92:95], v[140:143], v[196:199], v[92:95]
	v_mfma_f32_16x16x32_bf16 v[96:99], v[144:147], v[192:195], v[96:99]
	v_mfma_f32_16x16x32_bf16 v[96:99], v[148:151], v[196:199], v[96:99]
	s_setprio 0
	s_setprio 1
	v_mfma_f32_16x16x32_bf16 v[100:103], v[152:155], v[168:171], v[100:103]
	v_mfma_f32_16x16x32_bf16 v[100:103], v[156:159], v[172:175], v[100:103]
	v_mfma_f32_16x16x32_bf16 v[104:107], v[160:163], v[168:171], v[104:107]
	v_mfma_f32_16x16x32_bf16 v[104:107], v[164:167], v[172:175], v[104:107]
	v_mfma_f32_16x16x32_bf16 v[108:111], v[152:155], v[176:179], v[108:111]
	v_mfma_f32_16x16x32_bf16 v[108:111], v[156:159], v[180:183], v[108:111]
	v_mfma_f32_16x16x32_bf16 v[112:115], v[160:163], v[176:179], v[112:115]
	v_mfma_f32_16x16x32_bf16 v[112:115], v[164:167], v[180:183], v[112:115]
	v_mfma_f32_16x16x32_bf16 v[116:119], v[152:155], v[184:187], v[116:119]
	v_mfma_f32_16x16x32_bf16 v[116:119], v[156:159], v[188:191], v[116:119]
	v_mfma_f32_16x16x32_bf16 v[120:123], v[160:163], v[184:187], v[120:123]
	v_mfma_f32_16x16x32_bf16 v[120:123], v[164:167], v[188:191], v[120:123]
	v_mfma_f32_16x16x32_bf16 v[124:127], v[152:155], v[192:195], v[124:127]
	v_mfma_f32_16x16x32_bf16 v[124:127], v[156:159], v[196:199], v[124:127]
	v_mfma_f32_16x16x32_bf16 v[128:131], v[160:163], v[192:195], v[128:131]
	v_mfma_f32_16x16x32_bf16 v[128:131], v[164:167], v[196:199], v[128:131]
	s_setprio 0
	s_barrier
	ds_read_b128 v[136:139], v134
	ds_read_b128 v[140:143], v134 offset:1024
	ds_read_b128 v[144:147], v134 offset:2048
	ds_read_b128 v[148:151], v134 offset:3072
	ds_read_b128 v[152:155], v135
	ds_read_b128 v[156:159], v135 offset:1024
	ds_read_b128 v[160:163], v135 offset:2048
	ds_read_b128 v[164:167], v135 offset:3072
	s_mov_b32 m0, s7
	s_mov_b64 s[8:9], s[20:21]
	ds_read_b128 v[168:171], v246 offset:32768
	ds_read_b128 v[172:175], v246 offset:33792
	ds_read_b128 v[176:179], v246 offset:34816
	ds_read_b128 v[180:183], v246 offset:35840
	ds_read_b128 v[184:187], v246 offset:36864
	global_load_lds_dwordx4 v242, s[8:9]
	s_mov_b32 m0, s58
	ds_read_b128 v[188:191], v246 offset:37888
	global_load_lds_dwordx4 v2, s[8:9]
	s_add_u32 s8, s20, s46
	s_addc_u32 s9, s21, s47
	s_mov_b32 m0, s59
	ds_read_b128 v[192:195], v246 offset:38912
	global_load_lds_dwordx4 v242, s[8:9]
	s_mov_b32 m0, s69
	ds_read_b128 v[196:199], v246 offset:39936
	global_load_lds_dwordx4 v2, s[8:9]
	s_waitcnt vmcnt(8)
	s_waitcnt lgkmcnt(0)
	s_barrier
	s_setprio 1
	s_waitcnt lgkmcnt(0)
	v_mfma_f32_16x16x32_bf16 v[4:7], v[136:139], v[168:171], v[4:7]
	v_mfma_f32_16x16x32_bf16 v[4:7], v[140:143], v[172:175], v[4:7]
	v_mfma_f32_16x16x32_bf16 v[8:11], v[144:147], v[168:171], v[8:11]
	v_mfma_f32_16x16x32_bf16 v[8:11], v[148:151], v[172:175], v[8:11]
	v_mfma_f32_16x16x32_bf16 v[12:15], v[136:139], v[176:179], v[12:15]
	v_mfma_f32_16x16x32_bf16 v[12:15], v[140:143], v[180:183], v[12:15]
	v_mfma_f32_16x16x32_bf16 v[16:19], v[144:147], v[176:179], v[16:19]
	v_mfma_f32_16x16x32_bf16 v[16:19], v[148:151], v[180:183], v[16:19]
	v_mfma_f32_16x16x32_bf16 v[20:23], v[136:139], v[184:187], v[20:23]
	v_mfma_f32_16x16x32_bf16 v[20:23], v[140:143], v[188:191], v[20:23]
	v_mfma_f32_16x16x32_bf16 v[24:27], v[144:147], v[184:187], v[24:27]
	v_mfma_f32_16x16x32_bf16 v[24:27], v[148:151], v[188:191], v[24:27]
	v_mfma_f32_16x16x32_bf16 v[28:31], v[136:139], v[192:195], v[28:31]
	v_mfma_f32_16x16x32_bf16 v[28:31], v[140:143], v[196:199], v[28:31]
	v_mfma_f32_16x16x32_bf16 v[32:35], v[144:147], v[192:195], v[32:35]
	v_mfma_f32_16x16x32_bf16 v[32:35], v[148:151], v[196:199], v[32:35]
	s_setprio 0
	s_setprio 1
	v_mfma_f32_16x16x32_bf16 v[36:39], v[152:155], v[168:171], v[36:39]
	v_mfma_f32_16x16x32_bf16 v[36:39], v[156:159], v[172:175], v[36:39]
	v_mfma_f32_16x16x32_bf16 v[40:43], v[160:163], v[168:171], v[40:43]
	v_mfma_f32_16x16x32_bf16 v[40:43], v[164:167], v[172:175], v[40:43]
	v_mfma_f32_16x16x32_bf16 v[44:47], v[152:155], v[176:179], v[44:47]
	v_mfma_f32_16x16x32_bf16 v[44:47], v[156:159], v[180:183], v[44:47]
	v_mfma_f32_16x16x32_bf16 v[48:51], v[160:163], v[176:179], v[48:51]
	v_mfma_f32_16x16x32_bf16 v[48:51], v[164:167], v[180:183], v[48:51]
	v_mfma_f32_16x16x32_bf16 v[52:55], v[152:155], v[184:187], v[52:55]
	v_mfma_f32_16x16x32_bf16 v[52:55], v[156:159], v[188:191], v[52:55]
	v_mfma_f32_16x16x32_bf16 v[56:59], v[160:163], v[184:187], v[56:59]
	v_mfma_f32_16x16x32_bf16 v[56:59], v[164:167], v[188:191], v[56:59]
	v_mfma_f32_16x16x32_bf16 v[60:63], v[152:155], v[192:195], v[60:63]
	v_mfma_f32_16x16x32_bf16 v[60:63], v[156:159], v[196:199], v[60:63]
	v_mfma_f32_16x16x32_bf16 v[64:67], v[160:163], v[192:195], v[64:67]
	v_mfma_f32_16x16x32_bf16 v[64:67], v[164:167], v[196:199], v[64:67]
	s_setprio 0
	s_barrier
	s_mov_b32 m0, s84
	s_mov_b64 s[8:9], s[18:19]
	ds_read_b128 v[168:171], v246 offset:49152
	ds_read_b128 v[172:175], v246 offset:50176
	ds_read_b128 v[176:179], v246 offset:51200
	ds_read_b128 v[180:183], v246 offset:52224
	ds_read_b128 v[184:187], v246 offset:53248
	global_load_lds_dwordx4 v248, s[8:9]
	s_mov_b32 m0, s85
	ds_read_b128 v[188:191], v246 offset:54272
	global_load_lds_dwordx4 v247, s[8:9]
	s_add_u32 s8, s18, s46
	s_addc_u32 s9, s19, s47
	s_mov_b32 m0, s28
	ds_read_b128 v[192:195], v246 offset:55296
	global_load_lds_dwordx4 v248, s[8:9]
	s_mov_b32 m0, s29
	ds_read_b128 v[196:199], v246 offset:56320
	global_load_lds_dwordx4 v247, s[8:9]
	s_waitcnt vmcnt(6)
	s_waitcnt lgkmcnt(0)
	s_barrier
	s_setprio 1
	s_waitcnt lgkmcnt(0)
	v_mfma_f32_16x16x32_bf16 v[68:71], v[136:139], v[168:171], v[68:71]
	v_mfma_f32_16x16x32_bf16 v[68:71], v[140:143], v[172:175], v[68:71]
	v_mfma_f32_16x16x32_bf16 v[72:75], v[144:147], v[168:171], v[72:75]
	v_mfma_f32_16x16x32_bf16 v[72:75], v[148:151], v[172:175], v[72:75]
	v_mfma_f32_16x16x32_bf16 v[76:79], v[136:139], v[176:179], v[76:79]
	v_mfma_f32_16x16x32_bf16 v[76:79], v[140:143], v[180:183], v[76:79]
	v_mfma_f32_16x16x32_bf16 v[80:83], v[144:147], v[176:179], v[80:83]
	v_mfma_f32_16x16x32_bf16 v[80:83], v[148:151], v[180:183], v[80:83]
	v_mfma_f32_16x16x32_bf16 v[84:87], v[136:139], v[184:187], v[84:87]
	v_mfma_f32_16x16x32_bf16 v[84:87], v[140:143], v[188:191], v[84:87]
	v_mfma_f32_16x16x32_bf16 v[88:91], v[144:147], v[184:187], v[88:91]
	v_mfma_f32_16x16x32_bf16 v[88:91], v[148:151], v[188:191], v[88:91]
	v_mfma_f32_16x16x32_bf16 v[92:95], v[136:139], v[192:195], v[92:95]
	v_mfma_f32_16x16x32_bf16 v[92:95], v[140:143], v[196:199], v[92:95]
	v_mfma_f32_16x16x32_bf16 v[96:99], v[144:147], v[192:195], v[96:99]
	v_mfma_f32_16x16x32_bf16 v[96:99], v[148:151], v[196:199], v[96:99]
	s_setprio 0
	s_setprio 1
	v_mfma_f32_16x16x32_bf16 v[100:103], v[152:155], v[168:171], v[100:103]
	v_mfma_f32_16x16x32_bf16 v[100:103], v[156:159], v[172:175], v[100:103]
	v_mfma_f32_16x16x32_bf16 v[104:107], v[160:163], v[168:171], v[104:107]
	v_mfma_f32_16x16x32_bf16 v[104:107], v[164:167], v[172:175], v[104:107]
	v_mfma_f32_16x16x32_bf16 v[108:111], v[152:155], v[176:179], v[108:111]
	v_mfma_f32_16x16x32_bf16 v[108:111], v[156:159], v[180:183], v[108:111]
	v_mfma_f32_16x16x32_bf16 v[112:115], v[160:163], v[176:179], v[112:115]
	v_mfma_f32_16x16x32_bf16 v[112:115], v[164:167], v[180:183], v[112:115]
	v_mfma_f32_16x16x32_bf16 v[116:119], v[152:155], v[184:187], v[116:119]
	v_mfma_f32_16x16x32_bf16 v[116:119], v[156:159], v[188:191], v[116:119]
	v_mfma_f32_16x16x32_bf16 v[120:123], v[160:163], v[184:187], v[120:123]
	v_mfma_f32_16x16x32_bf16 v[120:123], v[164:167], v[188:191], v[120:123]
	v_mfma_f32_16x16x32_bf16 v[124:127], v[152:155], v[192:195], v[124:127]
	v_mfma_f32_16x16x32_bf16 v[124:127], v[156:159], v[196:199], v[124:127]
	v_mfma_f32_16x16x32_bf16 v[128:131], v[160:163], v[192:195], v[128:131]
	v_mfma_f32_16x16x32_bf16 v[128:131], v[164:167], v[196:199], v[128:131]
	s_setprio 0
	s_barrier
	s_add_i32 s8, s88, 2
	s_add_u32 s86, s86, 0x100
	s_addc_u32 s87, s87, 0
	s_add_u32 s26, s26, 0x100
	s_addc_u32 s27, s27, 0
	s_cmp_ge_i32 s88, s4
	s_mov_b32 s88, s8
	s_cbranch_scc0 .LBB0_880

.LBB0_1021:
	ds_read_b128 v[144:147], v132
	ds_read_b128 v[148:151], v132 offset:1024
	ds_read_b128 v[152:155], v132 offset:2048
	ds_read_b128 v[156:159], v132 offset:3072
	ds_read_b128 v[160:163], v133
	ds_read_b128 v[164:167], v133 offset:1024
	ds_read_b128 v[168:171], v133 offset:2048
	ds_read_b128 v[172:175], v133 offset:3072
	s_cmp_eq_u32 s76, s97
	s_cselect_b32 s17, s43, s96
	s_cselect_b32 s16, s42, s95
	s_cselect_b32 s67, s65, s73
	s_cselect_b32 s66, s64, s72
	s_add_u32 s8, s72, 0xffffff80
	s_addc_u32 s9, s73, -1
	s_mov_b32 m0, s85
	s_mov_b64 s[18:19], s[8:9]
	ds_read_b128 v[176:179], v141 offset:8192
	ds_read_b128 v[180:183], v141 offset:9216
	ds_read_b128 v[184:187], v141 offset:10240
	ds_read_b128 v[188:191], v141 offset:11264
	ds_read_b128 v[192:195], v141 offset:12288
	ds_read_b128 v[196:199], v141 offset:13312
	ds_read_b128 v[200:203], v141 offset:14336
	ds_read_b128 v[204:207], v141 offset:15360
	s_add_u32 s8, s8, s20
	global_load_lds_dwordx4 v137, s[18:19]
	s_mov_b32 m0, s86
	s_addc_u32 s9, s9, s21
	global_load_lds_dwordx4 v136, s[18:19]
	s_mov_b32 m0, s87
	s_add_u32 s18, s16, 0x80
	global_load_lds_dwordx4 v137, s[8:9]
	s_mov_b32 m0, s88
	s_addc_u32 s19, s17, 0
	global_load_lds_dwordx4 v136, s[8:9]
	s_waitcnt vmcnt(8)
	s_waitcnt lgkmcnt(0)
	s_barrier
	s_setprio 1
	s_waitcnt lgkmcnt(0)
	v_mfma_f32_16x16x32_bf16 v[4:7], v[144:147], v[176:179], v[4:7]
	v_mfma_f32_16x16x32_bf16 v[4:7], v[148:151], v[180:183], v[4:7]
	v_mfma_f32_16x16x32_bf16 v[8:11], v[152:155], v[176:179], v[8:11]
	v_mfma_f32_16x16x32_bf16 v[8:11], v[156:159], v[180:183], v[8:11]
	v_mfma_f32_16x16x32_bf16 v[12:15], v[144:147], v[184:187], v[12:15]
	v_mfma_f32_16x16x32_bf16 v[12:15], v[148:151], v[188:191], v[12:15]
	v_mfma_f32_16x16x32_bf16 v[16:19], v[152:155], v[184:187], v[16:19]
	v_mfma_f32_16x16x32_bf16 v[16:19], v[156:159], v[188:191], v[16:19]
	v_mfma_f32_16x16x32_bf16 v[20:23], v[144:147], v[192:195], v[20:23]
	v_mfma_f32_16x16x32_bf16 v[20:23], v[148:151], v[196:199], v[20:23]
	v_mfma_f32_16x16x32_bf16 v[24:27], v[152:155], v[192:195], v[24:27]
	v_mfma_f32_16x16x32_bf16 v[24:27], v[156:159], v[196:199], v[24:27]
	v_mfma_f32_16x16x32_bf16 v[28:31], v[144:147], v[200:203], v[28:31]
	v_mfma_f32_16x16x32_bf16 v[28:31], v[148:151], v[204:207], v[28:31]
	v_mfma_f32_16x16x32_bf16 v[32:35], v[152:155], v[200:203], v[32:35]
	v_mfma_f32_16x16x32_bf16 v[32:35], v[156:159], v[204:207], v[32:35]
	s_setprio 0
	s_setprio 1
	v_mfma_f32_16x16x32_bf16 v[36:39], v[160:163], v[176:179], v[36:39]
	v_mfma_f32_16x16x32_bf16 v[36:39], v[164:167], v[180:183], v[36:39]
	v_mfma_f32_16x16x32_bf16 v[40:43], v[168:171], v[176:179], v[40:43]
	v_mfma_f32_16x16x32_bf16 v[40:43], v[172:175], v[180:183], v[40:43]
	v_mfma_f32_16x16x32_bf16 v[44:47], v[160:163], v[184:187], v[44:47]
	v_mfma_f32_16x16x32_bf16 v[44:47], v[164:167], v[188:191], v[44:47]
	v_mfma_f32_16x16x32_bf16 v[48:51], v[168:171], v[184:187], v[48:51]
	v_mfma_f32_16x16x32_bf16 v[48:51], v[172:175], v[188:191], v[48:51]
	v_mfma_f32_16x16x32_bf16 v[52:55], v[160:163], v[192:195], v[52:55]
	v_mfma_f32_16x16x32_bf16 v[52:55], v[164:167], v[196:199], v[52:55]
	v_mfma_f32_16x16x32_bf16 v[56:59], v[168:171], v[192:195], v[56:59]
	v_mfma_f32_16x16x32_bf16 v[56:59], v[172:175], v[196:199], v[56:59]
	v_mfma_f32_16x16x32_bf16 v[60:63], v[160:163], v[200:203], v[60:63]
	v_mfma_f32_16x16x32_bf16 v[60:63], v[164:167], v[204:207], v[60:63]
	v_mfma_f32_16x16x32_bf16 v[64:67], v[168:171], v[200:203], v[64:67]
	v_mfma_f32_16x16x32_bf16 v[64:67], v[172:175], v[204:207], v[64:67]
	s_setprio 0
	s_barrier
	s_mov_b32 m0, s89
	s_mov_b64 s[8:9], s[16:17]
	ds_read_b128 v[176:179], v141 offset:24576
	ds_read_b128 v[180:183], v141 offset:25600
	ds_read_b128 v[184:187], v141 offset:26624
	ds_read_b128 v[188:191], v141 offset:27648
	ds_read_b128 v[192:195], v141 offset:28672
	global_load_lds_dwordx4 v143, s[8:9]
	s_mov_b32 m0, s90
	ds_read_b128 v[196:199], v141 offset:29696
	global_load_lds_dwordx4 v142, s[8:9]
	s_add_u32 s8, s16, s20
	s_addc_u32 s9, s17, s21
	s_mov_b32 m0, s91
	ds_read_b128 v[200:203], v141 offset:30720
	global_load_lds_dwordx4 v143, s[8:9]
	s_mov_b32 m0, s92
	ds_read_b128 v[204:207], v141 offset:31744
	global_load_lds_dwordx4 v142, s[8:9]
	s_waitcnt vmcnt(6)
	s_waitcnt lgkmcnt(0)
	s_barrier
	s_setprio 1
	s_waitcnt lgkmcnt(0)
	v_mfma_f32_16x16x32_bf16 v[68:71], v[144:147], v[176:179], v[68:71]
	v_mfma_f32_16x16x32_bf16 v[68:71], v[148:151], v[180:183], v[68:71]
	v_mfma_f32_16x16x32_bf16 v[72:75], v[152:155], v[176:179], v[72:75]
	v_mfma_f32_16x16x32_bf16 v[72:75], v[156:159], v[180:183], v[72:75]
	v_mfma_f32_16x16x32_bf16 v[76:79], v[144:147], v[184:187], v[76:79]
	v_mfma_f32_16x16x32_bf16 v[76:79], v[148:151], v[188:191], v[76:79]
	v_mfma_f32_16x16x32_bf16 v[80:83], v[152:155], v[184:187], v[80:83]
	v_mfma_f32_16x16x32_bf16 v[80:83], v[156:159], v[188:191], v[80:83]
	v_mfma_f32_16x16x32_bf16 v[84:87], v[144:147], v[192:195], v[84:87]
	v_mfma_f32_16x16x32_bf16 v[84:87], v[148:151], v[196:199], v[84:87]
	v_mfma_f32_16x16x32_bf16 v[88:91], v[152:155], v[192:195], v[88:91]
	v_mfma_f32_16x16x32_bf16 v[88:91], v[156:159], v[196:199], v[88:91]
	v_mfma_f32_16x16x32_bf16 v[92:95], v[144:147], v[200:203], v[92:95]
	v_mfma_f32_16x16x32_bf16 v[92:95], v[148:151], v[204:207], v[92:95]
	v_mfma_f32_16x16x32_bf16 v[96:99], v[152:155], v[200:203], v[96:99]
	v_mfma_f32_16x16x32_bf16 v[96:99], v[156:159], v[204:207], v[96:99]
	s_setprio 0
	s_setprio 1
	v_mfma_f32_16x16x32_bf16 v[100:103], v[160:163], v[176:179], v[100:103]
	v_mfma_f32_16x16x32_bf16 v[100:103], v[164:167], v[180:183], v[100:103]
	v_mfma_f32_16x16x32_bf16 v[104:107], v[168:171], v[176:179], v[104:107]
	v_mfma_f32_16x16x32_bf16 v[104:107], v[172:175], v[180:183], v[104:107]
	v_mfma_f32_16x16x32_bf16 v[108:111], v[160:163], v[184:187], v[108:111]
	v_mfma_f32_16x16x32_bf16 v[108:111], v[164:167], v[188:191], v[108:111]
	v_mfma_f32_16x16x32_bf16 v[112:115], v[168:171], v[184:187], v[112:115]
	v_mfma_f32_16x16x32_bf16 v[112:115], v[172:175], v[188:191], v[112:115]
	v_mfma_f32_16x16x32_bf16 v[116:119], v[160:163], v[192:195], v[116:119]
	v_mfma_f32_16x16x32_bf16 v[116:119], v[164:167], v[196:199], v[116:119]
	v_mfma_f32_16x16x32_bf16 v[120:123], v[168:171], v[192:195], v[120:123]
	v_mfma_f32_16x16x32_bf16 v[120:123], v[172:175], v[196:199], v[120:123]
	v_mfma_f32_16x16x32_bf16 v[124:127], v[160:163], v[200:203], v[124:127]
	v_mfma_f32_16x16x32_bf16 v[124:127], v[164:167], v[204:207], v[124:127]
	v_mfma_f32_16x16x32_bf16 v[128:131], v[168:171], v[200:203], v[128:131]
	v_mfma_f32_16x16x32_bf16 v[128:131], v[172:175], v[204:207], v[128:131]
	s_setprio 0
	s_barrier
	ds_read_b128 v[144:147], v134
	ds_read_b128 v[148:151], v134 offset:1024
	ds_read_b128 v[152:155], v134 offset:2048
	ds_read_b128 v[156:159], v134 offset:3072
	ds_read_b128 v[160:163], v135
	ds_read_b128 v[164:167], v135 offset:1024
	ds_read_b128 v[168:171], v135 offset:2048
	ds_read_b128 v[172:175], v135 offset:3072
	s_mov_b32 m0, s78
	s_mov_b64 s[8:9], s[66:67]
	ds_read_b128 v[176:179], v141 offset:40960
	ds_read_b128 v[180:183], v141 offset:41984
	ds_read_b128 v[184:187], v141 offset:43008
	ds_read_b128 v[188:191], v141 offset:44032
	ds_read_b128 v[192:195], v141 offset:45056
	global_load_lds_dwordx4 v137, s[8:9]
	s_mov_b32 m0, s79
	ds_read_b128 v[196:199], v141 offset:46080
	global_load_lds_dwordx4 v136, s[8:9]
	s_add_u32 s8, s66, s20
	s_addc_u32 s9, s67, s21
	s_mov_b32 m0, s80
	ds_read_b128 v[200:203], v141 offset:47104
	global_load_lds_dwordx4 v137, s[8:9]
	s_mov_b32 m0, s81
	ds_read_b128 v[204:207], v141 offset:48128
	global_load_lds_dwordx4 v136, s[8:9]
	s_waitcnt vmcnt(8)
	s_waitcnt lgkmcnt(0)
	s_barrier
	s_setprio 1
	s_waitcnt lgkmcnt(0)
	v_mfma_f32_16x16x32_bf16 v[4:7], v[144:147], v[176:179], v[4:7]
	v_mfma_f32_16x16x32_bf16 v[4:7], v[148:151], v[180:183], v[4:7]
	v_mfma_f32_16x16x32_bf16 v[8:11], v[152:155], v[176:179], v[8:11]
	v_mfma_f32_16x16x32_bf16 v[8:11], v[156:159], v[180:183], v[8:11]
	v_mfma_f32_16x16x32_bf16 v[12:15], v[144:147], v[184:187], v[12:15]
	v_mfma_f32_16x16x32_bf16 v[12:15], v[148:151], v[188:191], v[12:15]
	v_mfma_f32_16x16x32_bf16 v[16:19], v[152:155], v[184:187], v[16:19]
	v_mfma_f32_16x16x32_bf16 v[16:19], v[156:159], v[188:191], v[16:19]
	v_mfma_f32_16x16x32_bf16 v[20:23], v[144:147], v[192:195], v[20:23]
	v_mfma_f32_16x16x32_bf16 v[20:23], v[148:151], v[196:199], v[20:23]
	v_mfma_f32_16x16x32_bf16 v[24:27], v[152:155], v[192:195], v[24:27]
	v_mfma_f32_16x16x32_bf16 v[24:27], v[156:159], v[196:199], v[24:27]
	v_mfma_f32_16x16x32_bf16 v[28:31], v[144:147], v[200:203], v[28:31]
	v_mfma_f32_16x16x32_bf16 v[28:31], v[148:151], v[204:207], v[28:31]
	v_mfma_f32_16x16x32_bf16 v[32:35], v[152:155], v[200:203], v[32:35]
	v_mfma_f32_16x16x32_bf16 v[32:35], v[156:159], v[204:207], v[32:35]
	s_setprio 0
	s_setprio 1
	v_mfma_f32_16x16x32_bf16 v[36:39], v[160:163], v[176:179], v[36:39]
	v_mfma_f32_16x16x32_bf16 v[36:39], v[164:167], v[180:183], v[36:39]
	v_mfma_f32_16x16x32_bf16 v[40:43], v[168:171], v[176:179], v[40:43]
	v_mfma_f32_16x16x32_bf16 v[40:43], v[172:175], v[180:183], v[40:43]
	v_mfma_f32_16x16x32_bf16 v[44:47], v[160:163], v[184:187], v[44:47]
	v_mfma_f32_16x16x32_bf16 v[44:47], v[164:167], v[188:191], v[44:47]
	v_mfma_f32_16x16x32_bf16 v[48:51], v[168:171], v[184:187], v[48:51]
	v_mfma_f32_16x16x32_bf16 v[48:51], v[172:175], v[188:191], v[48:51]
	v_mfma_f32_16x16x32_bf16 v[52:55], v[160:163], v[192:195], v[52:55]
	v_mfma_f32_16x16x32_bf16 v[52:55], v[164:167], v[196:199], v[52:55]
	v_mfma_f32_16x16x32_bf16 v[56:59], v[168:171], v[192:195], v[56:59]
	v_mfma_f32_16x16x32_bf16 v[56:59], v[172:175], v[196:199], v[56:59]
	v_mfma_f32_16x16x32_bf16 v[60:63], v[160:163], v[200:203], v[60:63]
	v_mfma_f32_16x16x32_bf16 v[60:63], v[164:167], v[204:207], v[60:63]
	v_mfma_f32_16x16x32_bf16 v[64:67], v[168:171], v[200:203], v[64:67]
	v_mfma_f32_16x16x32_bf16 v[64:67], v[172:175], v[204:207], v[64:67]
	s_setprio 0
	s_barrier
	s_mov_b32 m0, s68
	s_mov_b64 s[8:9], s[18:19]
	ds_read_b128 v[176:179], v141 offset:57344
	ds_read_b128 v[180:183], v141 offset:58368
	ds_read_b128 v[184:187], v141 offset:59392
	ds_read_b128 v[188:191], v141 offset:60416
	ds_read_b128 v[192:195], v141 offset:61440
	global_load_lds_dwordx4 v143, s[8:9]
	s_mov_b32 m0, s69
	ds_read_b128 v[196:199], v141 offset:62464
	global_load_lds_dwordx4 v142, s[8:9]
	s_add_u32 s8, s18, s20
	s_addc_u32 s9, s19, s21
	s_mov_b32 m0, s93
	ds_read_b128 v[200:203], v141 offset:63488
	global_load_lds_dwordx4 v143, s[8:9]
	s_mov_b32 m0, s94
	ds_read_b128 v[204:207], v141 offset:64512
	global_load_lds_dwordx4 v142, s[8:9]
	s_waitcnt vmcnt(6)
	s_waitcnt lgkmcnt(0)
	s_barrier
	s_setprio 1
	s_waitcnt lgkmcnt(0)
	v_mfma_f32_16x16x32_bf16 v[68:71], v[144:147], v[176:179], v[68:71]
	v_mfma_f32_16x16x32_bf16 v[68:71], v[148:151], v[180:183], v[68:71]
	v_mfma_f32_16x16x32_bf16 v[72:75], v[152:155], v[176:179], v[72:75]
	v_mfma_f32_16x16x32_bf16 v[72:75], v[156:159], v[180:183], v[72:75]
	v_mfma_f32_16x16x32_bf16 v[76:79], v[144:147], v[184:187], v[76:79]
	v_mfma_f32_16x16x32_bf16 v[76:79], v[148:151], v[188:191], v[76:79]
	v_mfma_f32_16x16x32_bf16 v[80:83], v[152:155], v[184:187], v[80:83]
	v_mfma_f32_16x16x32_bf16 v[80:83], v[156:159], v[188:191], v[80:83]
	v_mfma_f32_16x16x32_bf16 v[84:87], v[144:147], v[192:195], v[84:87]
	v_mfma_f32_16x16x32_bf16 v[84:87], v[148:151], v[196:199], v[84:87]
	v_mfma_f32_16x16x32_bf16 v[88:91], v[152:155], v[192:195], v[88:91]
	v_mfma_f32_16x16x32_bf16 v[88:91], v[156:159], v[196:199], v[88:91]
	v_mfma_f32_16x16x32_bf16 v[92:95], v[144:147], v[200:203], v[92:95]
	v_mfma_f32_16x16x32_bf16 v[92:95], v[148:151], v[204:207], v[92:95]
	v_mfma_f32_16x16x32_bf16 v[96:99], v[152:155], v[200:203], v[96:99]
	v_mfma_f32_16x16x32_bf16 v[96:99], v[156:159], v[204:207], v[96:99]
	s_setprio 0
	s_setprio 1
	v_mfma_f32_16x16x32_bf16 v[100:103], v[160:163], v[176:179], v[100:103]
	v_mfma_f32_16x16x32_bf16 v[100:103], v[164:167], v[180:183], v[100:103]
	v_mfma_f32_16x16x32_bf16 v[104:107], v[168:171], v[176:179], v[104:107]
	v_mfma_f32_16x16x32_bf16 v[104:107], v[172:175], v[180:183], v[104:107]
	v_mfma_f32_16x16x32_bf16 v[108:111], v[160:163], v[184:187], v[108:111]
	v_mfma_f32_16x16x32_bf16 v[108:111], v[164:167], v[188:191], v[108:111]
	v_mfma_f32_16x16x32_bf16 v[112:115], v[168:171], v[184:187], v[112:115]
	v_mfma_f32_16x16x32_bf16 v[112:115], v[172:175], v[188:191], v[112:115]
	v_mfma_f32_16x16x32_bf16 v[116:119], v[160:163], v[192:195], v[116:119]
	v_mfma_f32_16x16x32_bf16 v[116:119], v[164:167], v[196:199], v[116:119]
	v_mfma_f32_16x16x32_bf16 v[120:123], v[168:171], v[192:195], v[120:123]
	v_mfma_f32_16x16x32_bf16 v[120:123], v[172:175], v[196:199], v[120:123]
	v_mfma_f32_16x16x32_bf16 v[124:127], v[160:163], v[200:203], v[124:127]
	v_mfma_f32_16x16x32_bf16 v[124:127], v[164:167], v[204:207], v[124:127]
	v_mfma_f32_16x16x32_bf16 v[128:131], v[168:171], v[200:203], v[128:131]
	v_mfma_f32_16x16x32_bf16 v[128:131], v[172:175], v[204:207], v[128:131]
	s_setprio 0
	s_barrier
	s_add_i32 s8, s97, 2
	s_add_u32 s95, s95, 0x100
	s_addc_u32 s96, s96, 0
	s_add_u32 s72, s72, 0x100
	s_addc_u32 s73, s73, 0
	s_cmp_ge_i32 s97, s76
	s_mov_b32 s97, s8
	s_cbranch_scc0 .LBB0_1021
	v_readlane_b32 s96, v255, 41
	v_readlane_b32 s97, v255, 42

.LBB0_1042:
	ds_read_b128 v[144:147], v132
	ds_read_b128 v[148:151], v132 offset:1024
	ds_read_b128 v[152:155], v132 offset:2048
	ds_read_b128 v[156:159], v132 offset:3072
	ds_read_b128 v[160:163], v133
	ds_read_b128 v[164:167], v133 offset:1024
	ds_read_b128 v[168:171], v133 offset:2048
	ds_read_b128 v[172:175], v133 offset:3072
	s_cmp_eq_u32 s72, s95
	s_cselect_b32 s17, s43, s94
	s_cselect_b32 s16, s42, s93
	s_cselect_b32 s65, s41, s67
	s_cselect_b32 s64, s40, s66
	s_add_u32 s8, s66, 0xffffff80
	s_addc_u32 s9, s67, -1
	s_mov_b32 m0, s83
	s_mov_b64 s[18:19], s[8:9]
	ds_read_b128 v[176:179], v141
	ds_read_b128 v[180:183], v141 offset:1024
	ds_read_b128 v[184:187], v141 offset:2048
	ds_read_b128 v[188:191], v141 offset:3072
	ds_read_b128 v[192:195], v141 offset:4096
	ds_read_b128 v[196:199], v141 offset:5120
	ds_read_b128 v[200:203], v141 offset:6144
	ds_read_b128 v[204:207], v141 offset:7168
	s_add_u32 s8, s8, s20
	global_load_lds_dwordx4 v137, s[18:19]
	s_mov_b32 m0, s84
	s_addc_u32 s9, s9, s21
	global_load_lds_dwordx4 v136, s[18:19]
	s_mov_b32 m0, s85
	s_add_u32 s18, s16, 0x80
	global_load_lds_dwordx4 v137, s[8:9]
	s_mov_b32 m0, s86
	s_addc_u32 s19, s17, 0
	global_load_lds_dwordx4 v136, s[8:9]
	s_waitcnt vmcnt(8)
	s_waitcnt lgkmcnt(0)
	s_barrier
	s_setprio 1
	s_waitcnt lgkmcnt(0)
	v_mfma_f32_16x16x32_bf16 v[4:7], v[144:147], v[176:179], v[4:7]
	v_mfma_f32_16x16x32_bf16 v[4:7], v[148:151], v[180:183], v[4:7]
	v_mfma_f32_16x16x32_bf16 v[8:11], v[152:155], v[176:179], v[8:11]
	v_mfma_f32_16x16x32_bf16 v[8:11], v[156:159], v[180:183], v[8:11]
	v_mfma_f32_16x16x32_bf16 v[12:15], v[144:147], v[184:187], v[12:15]
	v_mfma_f32_16x16x32_bf16 v[12:15], v[148:151], v[188:191], v[12:15]
	v_mfma_f32_16x16x32_bf16 v[16:19], v[152:155], v[184:187], v[16:19]
	v_mfma_f32_16x16x32_bf16 v[16:19], v[156:159], v[188:191], v[16:19]
	v_mfma_f32_16x16x32_bf16 v[20:23], v[144:147], v[192:195], v[20:23]
	v_mfma_f32_16x16x32_bf16 v[20:23], v[148:151], v[196:199], v[20:23]
	v_mfma_f32_16x16x32_bf16 v[24:27], v[152:155], v[192:195], v[24:27]
	v_mfma_f32_16x16x32_bf16 v[24:27], v[156:159], v[196:199], v[24:27]
	v_mfma_f32_16x16x32_bf16 v[28:31], v[144:147], v[200:203], v[28:31]
	v_mfma_f32_16x16x32_bf16 v[28:31], v[148:151], v[204:207], v[28:31]
	v_mfma_f32_16x16x32_bf16 v[32:35], v[152:155], v[200:203], v[32:35]
	v_mfma_f32_16x16x32_bf16 v[32:35], v[156:159], v[204:207], v[32:35]
	s_setprio 0
	s_setprio 1
	v_mfma_f32_16x16x32_bf16 v[36:39], v[160:163], v[176:179], v[36:39]
	v_mfma_f32_16x16x32_bf16 v[36:39], v[164:167], v[180:183], v[36:39]
	v_mfma_f32_16x16x32_bf16 v[40:43], v[168:171], v[176:179], v[40:43]
	v_mfma_f32_16x16x32_bf16 v[40:43], v[172:175], v[180:183], v[40:43]
	v_mfma_f32_16x16x32_bf16 v[44:47], v[160:163], v[184:187], v[44:47]
	v_mfma_f32_16x16x32_bf16 v[44:47], v[164:167], v[188:191], v[44:47]
	v_mfma_f32_16x16x32_bf16 v[48:51], v[168:171], v[184:187], v[48:51]
	v_mfma_f32_16x16x32_bf16 v[48:51], v[172:175], v[188:191], v[48:51]
	v_mfma_f32_16x16x32_bf16 v[52:55], v[160:163], v[192:195], v[52:55]
	v_mfma_f32_16x16x32_bf16 v[52:55], v[164:167], v[196:199], v[52:55]
	v_mfma_f32_16x16x32_bf16 v[56:59], v[168:171], v[192:195], v[56:59]
	v_mfma_f32_16x16x32_bf16 v[56:59], v[172:175], v[196:199], v[56:59]
	v_mfma_f32_16x16x32_bf16 v[60:63], v[160:163], v[200:203], v[60:63]
	v_mfma_f32_16x16x32_bf16 v[60:63], v[164:167], v[204:207], v[60:63]
	v_mfma_f32_16x16x32_bf16 v[64:67], v[168:171], v[200:203], v[64:67]
	v_mfma_f32_16x16x32_bf16 v[64:67], v[172:175], v[204:207], v[64:67]
	s_setprio 0
	s_barrier
	s_mov_b32 m0, s87
	s_mov_b64 s[8:9], s[16:17]
	ds_read_b128 v[176:179], v141 offset:16384
	ds_read_b128 v[180:183], v141 offset:17408
	ds_read_b128 v[184:187], v141 offset:18432
	ds_read_b128 v[188:191], v141 offset:19456
	ds_read_b128 v[192:195], v141 offset:20480
	global_load_lds_dwordx4 v143, s[8:9]
	s_mov_b32 m0, s88
	ds_read_b128 v[196:199], v141 offset:21504
	global_load_lds_dwordx4 v142, s[8:9]
	s_add_u32 s8, s16, s20
	s_addc_u32 s9, s17, s21
	s_mov_b32 m0, s89
	ds_read_b128 v[200:203], v141 offset:22528
	global_load_lds_dwordx4 v143, s[8:9]
	s_mov_b32 m0, s90
	ds_read_b128 v[204:207], v141 offset:23552
	global_load_lds_dwordx4 v142, s[8:9]
	s_waitcnt vmcnt(6)
	s_waitcnt lgkmcnt(0)
	s_barrier
	s_setprio 1
	s_waitcnt lgkmcnt(0)
	v_mfma_f32_16x16x32_bf16 v[68:71], v[144:147], v[176:179], v[68:71]
	v_mfma_f32_16x16x32_bf16 v[68:71], v[148:151], v[180:183], v[68:71]
	v_mfma_f32_16x16x32_bf16 v[72:75], v[152:155], v[176:179], v[72:75]
	v_mfma_f32_16x16x32_bf16 v[72:75], v[156:159], v[180:183], v[72:75]
	v_mfma_f32_16x16x32_bf16 v[76:79], v[144:147], v[184:187], v[76:79]
	v_mfma_f32_16x16x32_bf16 v[76:79], v[148:151], v[188:191], v[76:79]
	v_mfma_f32_16x16x32_bf16 v[80:83], v[152:155], v[184:187], v[80:83]
	v_mfma_f32_16x16x32_bf16 v[80:83], v[156:159], v[188:191], v[80:83]
	v_mfma_f32_16x16x32_bf16 v[84:87], v[144:147], v[192:195], v[84:87]
	v_mfma_f32_16x16x32_bf16 v[84:87], v[148:151], v[196:199], v[84:87]
	v_mfma_f32_16x16x32_bf16 v[88:91], v[152:155], v[192:195], v[88:91]
	v_mfma_f32_16x16x32_bf16 v[88:91], v[156:159], v[196:199], v[88:91]
	v_mfma_f32_16x16x32_bf16 v[92:95], v[144:147], v[200:203], v[92:95]
	v_mfma_f32_16x16x32_bf16 v[92:95], v[148:151], v[204:207], v[92:95]
	v_mfma_f32_16x16x32_bf16 v[96:99], v[152:155], v[200:203], v[96:99]
	v_mfma_f32_16x16x32_bf16 v[96:99], v[156:159], v[204:207], v[96:99]
	s_setprio 0
	s_setprio 1
	v_mfma_f32_16x16x32_bf16 v[100:103], v[160:163], v[176:179], v[100:103]
	v_mfma_f32_16x16x32_bf16 v[100:103], v[164:167], v[180:183], v[100:103]
	v_mfma_f32_16x16x32_bf16 v[104:107], v[168:171], v[176:179], v[104:107]
	v_mfma_f32_16x16x32_bf16 v[104:107], v[172:175], v[180:183], v[104:107]
	v_mfma_f32_16x16x32_bf16 v[108:111], v[160:163], v[184:187], v[108:111]
	v_mfma_f32_16x16x32_bf16 v[108:111], v[164:167], v[188:191], v[108:111]
	v_mfma_f32_16x16x32_bf16 v[112:115], v[168:171], v[184:187], v[112:115]
	v_mfma_f32_16x16x32_bf16 v[112:115], v[172:175], v[188:191], v[112:115]
	v_mfma_f32_16x16x32_bf16 v[116:119], v[160:163], v[192:195], v[116:119]
	v_mfma_f32_16x16x32_bf16 v[116:119], v[164:167], v[196:199], v[116:119]
	v_mfma_f32_16x16x32_bf16 v[120:123], v[168:171], v[192:195], v[120:123]
	v_mfma_f32_16x16x32_bf16 v[120:123], v[172:175], v[196:199], v[120:123]
	v_mfma_f32_16x16x32_bf16 v[124:127], v[160:163], v[200:203], v[124:127]
	v_mfma_f32_16x16x32_bf16 v[124:127], v[164:167], v[204:207], v[124:127]
	v_mfma_f32_16x16x32_bf16 v[128:131], v[168:171], v[200:203], v[128:131]
	v_mfma_f32_16x16x32_bf16 v[128:131], v[172:175], v[204:207], v[128:131]
	s_setprio 0
	s_barrier
	ds_read_b128 v[144:147], v134
	ds_read_b128 v[148:151], v134 offset:1024
	ds_read_b128 v[152:155], v134 offset:2048
	ds_read_b128 v[156:159], v134 offset:3072
	ds_read_b128 v[160:163], v135
	ds_read_b128 v[164:167], v135 offset:1024
	ds_read_b128 v[168:171], v135 offset:2048
	ds_read_b128 v[172:175], v135 offset:3072
	s_mov_b32 m0, s76
	s_mov_b64 s[8:9], s[64:65]
	ds_read_b128 v[176:179], v141 offset:32768
	ds_read_b128 v[180:183], v141 offset:33792
	ds_read_b128 v[184:187], v141 offset:34816
	ds_read_b128 v[188:191], v141 offset:35840
	ds_read_b128 v[192:195], v141 offset:36864
	global_load_lds_dwordx4 v137, s[8:9]
	s_mov_b32 m0, s77
	ds_read_b128 v[196:199], v141 offset:37888
	global_load_lds_dwordx4 v136, s[8:9]
	s_add_u32 s8, s64, s20
	s_addc_u32 s9, s65, s21
	s_mov_b32 m0, s78
	ds_read_b128 v[200:203], v141 offset:38912
	global_load_lds_dwordx4 v137, s[8:9]
	s_mov_b32 m0, s79
	ds_read_b128 v[204:207], v141 offset:39936
	global_load_lds_dwordx4 v136, s[8:9]
	s_waitcnt vmcnt(8)
	s_waitcnt lgkmcnt(0)
	s_barrier
	s_setprio 1
	s_waitcnt lgkmcnt(0)
	v_mfma_f32_16x16x32_bf16 v[4:7], v[144:147], v[176:179], v[4:7]
	v_mfma_f32_16x16x32_bf16 v[4:7], v[148:151], v[180:183], v[4:7]
	v_mfma_f32_16x16x32_bf16 v[8:11], v[152:155], v[176:179], v[8:11]
	v_mfma_f32_16x16x32_bf16 v[8:11], v[156:159], v[180:183], v[8:11]
	v_mfma_f32_16x16x32_bf16 v[12:15], v[144:147], v[184:187], v[12:15]
	v_mfma_f32_16x16x32_bf16 v[12:15], v[148:151], v[188:191], v[12:15]
	v_mfma_f32_16x16x32_bf16 v[16:19], v[152:155], v[184:187], v[16:19]
	v_mfma_f32_16x16x32_bf16 v[16:19], v[156:159], v[188:191], v[16:19]
	v_mfma_f32_16x16x32_bf16 v[20:23], v[144:147], v[192:195], v[20:23]
	v_mfma_f32_16x16x32_bf16 v[20:23], v[148:151], v[196:199], v[20:23]
	v_mfma_f32_16x16x32_bf16 v[24:27], v[152:155], v[192:195], v[24:27]
	v_mfma_f32_16x16x32_bf16 v[24:27], v[156:159], v[196:199], v[24:27]
	v_mfma_f32_16x16x32_bf16 v[28:31], v[144:147], v[200:203], v[28:31]
	v_mfma_f32_16x16x32_bf16 v[28:31], v[148:151], v[204:207], v[28:31]
	v_mfma_f32_16x16x32_bf16 v[32:35], v[152:155], v[200:203], v[32:35]
	v_mfma_f32_16x16x32_bf16 v[32:35], v[156:159], v[204:207], v[32:35]
	s_setprio 0
	s_setprio 1
	v_mfma_f32_16x16x32_bf16 v[36:39], v[160:163], v[176:179], v[36:39]
	v_mfma_f32_16x16x32_bf16 v[36:39], v[164:167], v[180:183], v[36:39]
	v_mfma_f32_16x16x32_bf16 v[40:43], v[168:171], v[176:179], v[40:43]
	v_mfma_f32_16x16x32_bf16 v[40:43], v[172:175], v[180:183], v[40:43]
	v_mfma_f32_16x16x32_bf16 v[44:47], v[160:163], v[184:187], v[44:47]
	v_mfma_f32_16x16x32_bf16 v[44:47], v[164:167], v[188:191], v[44:47]
	v_mfma_f32_16x16x32_bf16 v[48:51], v[168:171], v[184:187], v[48:51]
	v_mfma_f32_16x16x32_bf16 v[48:51], v[172:175], v[188:191], v[48:51]
	v_mfma_f32_16x16x32_bf16 v[52:55], v[160:163], v[192:195], v[52:55]
	v_mfma_f32_16x16x32_bf16 v[52:55], v[164:167], v[196:199], v[52:55]
	v_mfma_f32_16x16x32_bf16 v[56:59], v[168:171], v[192:195], v[56:59]
	v_mfma_f32_16x16x32_bf16 v[56:59], v[172:175], v[196:199], v[56:59]
	v_mfma_f32_16x16x32_bf16 v[60:63], v[160:163], v[200:203], v[60:63]
	v_mfma_f32_16x16x32_bf16 v[60:63], v[164:167], v[204:207], v[60:63]
	v_mfma_f32_16x16x32_bf16 v[64:67], v[168:171], v[200:203], v[64:67]
	v_mfma_f32_16x16x32_bf16 v[64:67], v[172:175], v[204:207], v[64:67]
	s_setprio 0
	s_barrier
	s_mov_b32 m0, s68
	s_mov_b64 s[8:9], s[18:19]
	ds_read_b128 v[176:179], v141 offset:49152
	ds_read_b128 v[180:183], v141 offset:50176
	ds_read_b128 v[184:187], v141 offset:51200
	ds_read_b128 v[188:191], v141 offset:52224
	ds_read_b128 v[192:195], v141 offset:53248
	global_load_lds_dwordx4 v143, s[8:9]
	s_mov_b32 m0, s69
	ds_read_b128 v[196:199], v141 offset:54272
	global_load_lds_dwordx4 v142, s[8:9]
	s_add_u32 s8, s18, s20
	s_addc_u32 s9, s19, s21
	s_mov_b32 m0, s91
	ds_read_b128 v[200:203], v141 offset:55296
	global_load_lds_dwordx4 v143, s[8:9]
	s_mov_b32 m0, s92
	ds_read_b128 v[204:207], v141 offset:56320
	global_load_lds_dwordx4 v142, s[8:9]
	s_waitcnt vmcnt(6)
	s_waitcnt lgkmcnt(0)
	s_barrier
	s_setprio 1
	s_waitcnt lgkmcnt(0)
	v_mfma_f32_16x16x32_bf16 v[68:71], v[144:147], v[176:179], v[68:71]
	v_mfma_f32_16x16x32_bf16 v[68:71], v[148:151], v[180:183], v[68:71]
	v_mfma_f32_16x16x32_bf16 v[72:75], v[152:155], v[176:179], v[72:75]
	v_mfma_f32_16x16x32_bf16 v[72:75], v[156:159], v[180:183], v[72:75]
	v_mfma_f32_16x16x32_bf16 v[76:79], v[144:147], v[184:187], v[76:79]
	v_mfma_f32_16x16x32_bf16 v[76:79], v[148:151], v[188:191], v[76:79]
	v_mfma_f32_16x16x32_bf16 v[80:83], v[152:155], v[184:187], v[80:83]
	v_mfma_f32_16x16x32_bf16 v[80:83], v[156:159], v[188:191], v[80:83]
	v_mfma_f32_16x16x32_bf16 v[84:87], v[144:147], v[192:195], v[84:87]
	v_mfma_f32_16x16x32_bf16 v[84:87], v[148:151], v[196:199], v[84:87]
	v_mfma_f32_16x16x32_bf16 v[88:91], v[152:155], v[192:195], v[88:91]
	v_mfma_f32_16x16x32_bf16 v[88:91], v[156:159], v[196:199], v[88:91]
	v_mfma_f32_16x16x32_bf16 v[92:95], v[144:147], v[200:203], v[92:95]
	v_mfma_f32_16x16x32_bf16 v[92:95], v[148:151], v[204:207], v[92:95]
	v_mfma_f32_16x16x32_bf16 v[96:99], v[152:155], v[200:203], v[96:99]
	v_mfma_f32_16x16x32_bf16 v[96:99], v[156:159], v[204:207], v[96:99]
	s_setprio 0
	s_setprio 1
	v_mfma_f32_16x16x32_bf16 v[100:103], v[160:163], v[176:179], v[100:103]
	v_mfma_f32_16x16x32_bf16 v[100:103], v[164:167], v[180:183], v[100:103]
	v_mfma_f32_16x16x32_bf16 v[104:107], v[168:171], v[176:179], v[104:107]
	v_mfma_f32_16x16x32_bf16 v[104:107], v[172:175], v[180:183], v[104:107]
	v_mfma_f32_16x16x32_bf16 v[108:111], v[160:163], v[184:187], v[108:111]
	v_mfma_f32_16x16x32_bf16 v[108:111], v[164:167], v[188:191], v[108:111]
	v_mfma_f32_16x16x32_bf16 v[112:115], v[168:171], v[184:187], v[112:115]
	v_mfma_f32_16x16x32_bf16 v[112:115], v[172:175], v[188:191], v[112:115]
	v_mfma_f32_16x16x32_bf16 v[116:119], v[160:163], v[192:195], v[116:119]
	v_mfma_f32_16x16x32_bf16 v[116:119], v[164:167], v[196:199], v[116:119]
	v_mfma_f32_16x16x32_bf16 v[120:123], v[168:171], v[192:195], v[120:123]
	v_mfma_f32_16x16x32_bf16 v[120:123], v[172:175], v[196:199], v[120:123]
	v_mfma_f32_16x16x32_bf16 v[124:127], v[160:163], v[200:203], v[124:127]
	v_mfma_f32_16x16x32_bf16 v[124:127], v[164:167], v[204:207], v[124:127]
	v_mfma_f32_16x16x32_bf16 v[128:131], v[168:171], v[200:203], v[128:131]
	v_mfma_f32_16x16x32_bf16 v[128:131], v[172:175], v[204:207], v[128:131]
	s_setprio 0
	s_barrier
	s_add_i32 s8, s95, 2
	s_add_u32 s93, s93, 0x100
	s_addc_u32 s94, s94, 0
	s_add_u32 s66, s66, 0x100
	s_addc_u32 s67, s67, 0
	s_cmp_ge_i32 s95, s72
	s_mov_b32 s95, s8
	s_cbranch_scc0 .LBB0_1042
	v_readlane_b32 s94, v255, 39
	v_readlane_b32 s95, v255, 40
	s_branch .LBB0_1031

.LBB0_1156:
	ds_read_b128 v[136:139], v132
	ds_read_b128 v[140:143], v132 offset:1024
	ds_read_b128 v[144:147], v132 offset:2048
	ds_read_b128 v[148:151], v132 offset:3072
	ds_read_b128 v[152:155], v133
	ds_read_b128 v[156:159], v133 offset:1024
	ds_read_b128 v[160:163], v133 offset:2048
	ds_read_b128 v[164:167], v133 offset:3072
	s_cmp_eq_u32 s6, s82
	s_cselect_b32 s17, s27, s81
	s_cselect_b32 s16, s26, s80
	s_cselect_b32 s21, s51, s53
	s_cselect_b32 s20, s50, s52
	s_add_u32 s8, s52, 0xffffff80
	s_addc_u32 s9, s53, -1
	s_mov_b32 m0, s66
	s_mov_b64 s[18:19], s[8:9]
	ds_read_b128 v[168:171], v244 offset:8192
	ds_read_b128 v[172:175], v244 offset:9216
	ds_read_b128 v[176:179], v244 offset:10240
	ds_read_b128 v[180:183], v244 offset:11264
	ds_read_b128 v[184:187], v244 offset:12288
	ds_read_b128 v[188:191], v244 offset:13312
	ds_read_b128 v[192:195], v244 offset:14336
	ds_read_b128 v[196:199], v244 offset:15360
	s_add_u32 s8, s8, s28
	global_load_lds_dwordx4 v238, s[18:19]
	s_mov_b32 m0, s67
	s_addc_u32 s9, s9, s29
	global_load_lds_dwordx4 v2, s[18:19]
	s_mov_b32 m0, s68
	s_add_u32 s18, s16, 0x80
	global_load_lds_dwordx4 v238, s[8:9]
	s_mov_b32 m0, s69
	s_addc_u32 s19, s17, 0
	global_load_lds_dwordx4 v2, s[8:9]
	s_waitcnt vmcnt(8)
	s_waitcnt lgkmcnt(0)
	s_barrier
	s_setprio 1
	s_waitcnt lgkmcnt(0)
	v_mfma_f32_16x16x32_bf16 v[4:7], v[136:139], v[168:171], v[4:7]
	v_mfma_f32_16x16x32_bf16 v[4:7], v[140:143], v[172:175], v[4:7]
	v_mfma_f32_16x16x32_bf16 v[8:11], v[144:147], v[168:171], v[8:11]
	v_mfma_f32_16x16x32_bf16 v[8:11], v[148:151], v[172:175], v[8:11]
	v_mfma_f32_16x16x32_bf16 v[12:15], v[136:139], v[176:179], v[12:15]
	v_mfma_f32_16x16x32_bf16 v[12:15], v[140:143], v[180:183], v[12:15]
	v_mfma_f32_16x16x32_bf16 v[16:19], v[144:147], v[176:179], v[16:19]
	v_mfma_f32_16x16x32_bf16 v[16:19], v[148:151], v[180:183], v[16:19]
	v_mfma_f32_16x16x32_bf16 v[20:23], v[136:139], v[184:187], v[20:23]
	v_mfma_f32_16x16x32_bf16 v[20:23], v[140:143], v[188:191], v[20:23]
	v_mfma_f32_16x16x32_bf16 v[24:27], v[144:147], v[184:187], v[24:27]
	v_mfma_f32_16x16x32_bf16 v[24:27], v[148:151], v[188:191], v[24:27]
	v_mfma_f32_16x16x32_bf16 v[28:31], v[136:139], v[192:195], v[28:31]
	v_mfma_f32_16x16x32_bf16 v[28:31], v[140:143], v[196:199], v[28:31]
	v_mfma_f32_16x16x32_bf16 v[32:35], v[144:147], v[192:195], v[32:35]
	v_mfma_f32_16x16x32_bf16 v[32:35], v[148:151], v[196:199], v[32:35]
	s_setprio 0
	s_setprio 1
	v_mfma_f32_16x16x32_bf16 v[36:39], v[152:155], v[168:171], v[36:39]
	v_mfma_f32_16x16x32_bf16 v[36:39], v[156:159], v[172:175], v[36:39]
	v_mfma_f32_16x16x32_bf16 v[40:43], v[160:163], v[168:171], v[40:43]
	v_mfma_f32_16x16x32_bf16 v[40:43], v[164:167], v[172:175], v[40:43]
	v_mfma_f32_16x16x32_bf16 v[44:47], v[152:155], v[176:179], v[44:47]
	v_mfma_f32_16x16x32_bf16 v[44:47], v[156:159], v[180:183], v[44:47]
	v_mfma_f32_16x16x32_bf16 v[48:51], v[160:163], v[176:179], v[48:51]
	v_mfma_f32_16x16x32_bf16 v[48:51], v[164:167], v[180:183], v[48:51]
	v_mfma_f32_16x16x32_bf16 v[52:55], v[152:155], v[184:187], v[52:55]
	v_mfma_f32_16x16x32_bf16 v[52:55], v[156:159], v[188:191], v[52:55]
	v_mfma_f32_16x16x32_bf16 v[56:59], v[160:163], v[184:187], v[56:59]
	v_mfma_f32_16x16x32_bf16 v[56:59], v[164:167], v[188:191], v[56:59]
	v_mfma_f32_16x16x32_bf16 v[60:63], v[152:155], v[192:195], v[60:63]
	v_mfma_f32_16x16x32_bf16 v[60:63], v[156:159], v[196:199], v[60:63]
	v_mfma_f32_16x16x32_bf16 v[64:67], v[160:163], v[192:195], v[64:67]
	v_mfma_f32_16x16x32_bf16 v[64:67], v[164:167], v[196:199], v[64:67]
	s_setprio 0
	s_barrier
	s_mov_b32 m0, s72
	s_mov_b64 s[8:9], s[16:17]
	ds_read_b128 v[168:171], v244 offset:24576
	ds_read_b128 v[172:175], v244 offset:25600
	ds_read_b128 v[176:179], v244 offset:26624
	ds_read_b128 v[180:183], v244 offset:27648
	ds_read_b128 v[184:187], v244 offset:28672
	global_load_lds_dwordx4 v246, s[8:9]
	s_mov_b32 m0, s73
	ds_read_b128 v[188:191], v244 offset:29696
	global_load_lds_dwordx4 v245, s[8:9]
	s_add_u32 s8, s16, s28
	s_addc_u32 s9, s17, s29
	s_mov_b32 m0, s76
	ds_read_b128 v[192:195], v244 offset:30720
	global_load_lds_dwordx4 v246, s[8:9]
	s_mov_b32 m0, s77
	ds_read_b128 v[196:199], v244 offset:31744
	global_load_lds_dwordx4 v245, s[8:9]
	s_waitcnt vmcnt(6)
	s_waitcnt lgkmcnt(0)
	s_barrier
	s_setprio 1
	s_waitcnt lgkmcnt(0)
	v_mfma_f32_16x16x32_bf16 v[68:71], v[136:139], v[168:171], v[68:71]
	v_mfma_f32_16x16x32_bf16 v[68:71], v[140:143], v[172:175], v[68:71]
	v_mfma_f32_16x16x32_bf16 v[72:75], v[144:147], v[168:171], v[72:75]
	v_mfma_f32_16x16x32_bf16 v[72:75], v[148:151], v[172:175], v[72:75]
	v_mfma_f32_16x16x32_bf16 v[76:79], v[136:139], v[176:179], v[76:79]
	v_mfma_f32_16x16x32_bf16 v[76:79], v[140:143], v[180:183], v[76:79]
	v_mfma_f32_16x16x32_bf16 v[80:83], v[144:147], v[176:179], v[80:83]
	v_mfma_f32_16x16x32_bf16 v[80:83], v[148:151], v[180:183], v[80:83]
	v_mfma_f32_16x16x32_bf16 v[84:87], v[136:139], v[184:187], v[84:87]
	v_mfma_f32_16x16x32_bf16 v[84:87], v[140:143], v[188:191], v[84:87]
	v_mfma_f32_16x16x32_bf16 v[88:91], v[144:147], v[184:187], v[88:91]
	v_mfma_f32_16x16x32_bf16 v[88:91], v[148:151], v[188:191], v[88:91]
	v_mfma_f32_16x16x32_bf16 v[92:95], v[136:139], v[192:195], v[92:95]
	v_mfma_f32_16x16x32_bf16 v[92:95], v[140:143], v[196:199], v[92:95]
	v_mfma_f32_16x16x32_bf16 v[96:99], v[144:147], v[192:195], v[96:99]
	v_mfma_f32_16x16x32_bf16 v[96:99], v[148:151], v[196:199], v[96:99]
	s_setprio 0
	s_setprio 1
	v_mfma_f32_16x16x32_bf16 v[100:103], v[152:155], v[168:171], v[100:103]
	v_mfma_f32_16x16x32_bf16 v[100:103], v[156:159], v[172:175], v[100:103]
	v_mfma_f32_16x16x32_bf16 v[104:107], v[160:163], v[168:171], v[104:107]
	v_mfma_f32_16x16x32_bf16 v[104:107], v[164:167], v[172:175], v[104:107]
	v_mfma_f32_16x16x32_bf16 v[108:111], v[152:155], v[176:179], v[108:111]
	v_mfma_f32_16x16x32_bf16 v[108:111], v[156:159], v[180:183], v[108:111]
	v_mfma_f32_16x16x32_bf16 v[112:115], v[160:163], v[176:179], v[112:115]
	v_mfma_f32_16x16x32_bf16 v[112:115], v[164:167], v[180:183], v[112:115]
	v_mfma_f32_16x16x32_bf16 v[116:119], v[152:155], v[184:187], v[116:119]
	v_mfma_f32_16x16x32_bf16 v[116:119], v[156:159], v[188:191], v[116:119]
	v_mfma_f32_16x16x32_bf16 v[120:123], v[160:163], v[184:187], v[120:123]
	v_mfma_f32_16x16x32_bf16 v[120:123], v[164:167], v[188:191], v[120:123]
	v_mfma_f32_16x16x32_bf16 v[124:127], v[152:155], v[192:195], v[124:127]
	v_mfma_f32_16x16x32_bf16 v[124:127], v[156:159], v[196:199], v[124:127]
	v_mfma_f32_16x16x32_bf16 v[128:131], v[160:163], v[192:195], v[128:131]
	v_mfma_f32_16x16x32_bf16 v[128:131], v[164:167], v[196:199], v[128:131]
	s_setprio 0
	s_barrier
	ds_read_b128 v[136:139], v134
	ds_read_b128 v[140:143], v134 offset:1024
	ds_read_b128 v[144:147], v134 offset:2048
	ds_read_b128 v[148:151], v134 offset:3072
	ds_read_b128 v[152:155], v135
	ds_read_b128 v[156:159], v135 offset:1024
	ds_read_b128 v[160:163], v135 offset:2048
	ds_read_b128 v[164:167], v135 offset:3072
	s_mov_b32 m0, s58
	s_mov_b64 s[8:9], s[20:21]
	ds_read_b128 v[168:171], v244 offset:40960
	ds_read_b128 v[172:175], v244 offset:41984
	ds_read_b128 v[176:179], v244 offset:43008
	ds_read_b128 v[180:183], v244 offset:44032
	ds_read_b128 v[184:187], v244 offset:45056
	global_load_lds_dwordx4 v238, s[8:9]
	s_mov_b32 m0, s59
	ds_read_b128 v[188:191], v244 offset:46080
	global_load_lds_dwordx4 v2, s[8:9]
	s_add_u32 s8, s20, s28
	s_addc_u32 s9, s21, s29
	s_mov_b32 m0, s60
	ds_read_b128 v[192:195], v244 offset:47104
	global_load_lds_dwordx4 v238, s[8:9]
	s_mov_b32 m0, s61
	ds_read_b128 v[196:199], v244 offset:48128
	global_load_lds_dwordx4 v2, s[8:9]
	s_waitcnt vmcnt(8)
	s_waitcnt lgkmcnt(0)
	s_barrier
	s_setprio 1
	s_waitcnt lgkmcnt(0)
	v_mfma_f32_16x16x32_bf16 v[4:7], v[136:139], v[168:171], v[4:7]
	v_mfma_f32_16x16x32_bf16 v[4:7], v[140:143], v[172:175], v[4:7]
	v_mfma_f32_16x16x32_bf16 v[8:11], v[144:147], v[168:171], v[8:11]
	v_mfma_f32_16x16x32_bf16 v[8:11], v[148:151], v[172:175], v[8:11]
	v_mfma_f32_16x16x32_bf16 v[12:15], v[136:139], v[176:179], v[12:15]
	v_mfma_f32_16x16x32_bf16 v[12:15], v[140:143], v[180:183], v[12:15]
	v_mfma_f32_16x16x32_bf16 v[16:19], v[144:147], v[176:179], v[16:19]
	v_mfma_f32_16x16x32_bf16 v[16:19], v[148:151], v[180:183], v[16:19]
	v_mfma_f32_16x16x32_bf16 v[20:23], v[136:139], v[184:187], v[20:23]
	v_mfma_f32_16x16x32_bf16 v[20:23], v[140:143], v[188:191], v[20:23]
	v_mfma_f32_16x16x32_bf16 v[24:27], v[144:147], v[184:187], v[24:27]
	v_mfma_f32_16x16x32_bf16 v[24:27], v[148:151], v[188:191], v[24:27]
	v_mfma_f32_16x16x32_bf16 v[28:31], v[136:139], v[192:195], v[28:31]
	v_mfma_f32_16x16x32_bf16 v[28:31], v[140:143], v[196:199], v[28:31]
	v_mfma_f32_16x16x32_bf16 v[32:35], v[144:147], v[192:195], v[32:35]
	v_mfma_f32_16x16x32_bf16 v[32:35], v[148:151], v[196:199], v[32:35]
	s_setprio 0
	s_setprio 1
	v_mfma_f32_16x16x32_bf16 v[36:39], v[152:155], v[168:171], v[36:39]
	v_mfma_f32_16x16x32_bf16 v[36:39], v[156:159], v[172:175], v[36:39]
	v_mfma_f32_16x16x32_bf16 v[40:43], v[160:163], v[168:171], v[40:43]
	v_mfma_f32_16x16x32_bf16 v[40:43], v[164:167], v[172:175], v[40:43]
	v_mfma_f32_16x16x32_bf16 v[44:47], v[152:155], v[176:179], v[44:47]
	v_mfma_f32_16x16x32_bf16 v[44:47], v[156:159], v[180:183], v[44:47]
	v_mfma_f32_16x16x32_bf16 v[48:51], v[160:163], v[176:179], v[48:51]
	v_mfma_f32_16x16x32_bf16 v[48:51], v[164:167], v[180:183], v[48:51]
	v_mfma_f32_16x16x32_bf16 v[52:55], v[152:155], v[184:187], v[52:55]
	v_mfma_f32_16x16x32_bf16 v[52:55], v[156:159], v[188:191], v[52:55]
	v_mfma_f32_16x16x32_bf16 v[56:59], v[160:163], v[184:187], v[56:59]
	v_mfma_f32_16x16x32_bf16 v[56:59], v[164:167], v[188:191], v[56:59]
	v_mfma_f32_16x16x32_bf16 v[60:63], v[152:155], v[192:195], v[60:63]
	v_mfma_f32_16x16x32_bf16 v[60:63], v[156:159], v[196:199], v[60:63]
	v_mfma_f32_16x16x32_bf16 v[64:67], v[160:163], v[192:195], v[64:67]
	v_mfma_f32_16x16x32_bf16 v[64:67], v[164:167], v[196:199], v[64:67]
	s_setprio 0
	s_barrier
	s_mov_b32 m0, s42
	s_mov_b64 s[8:9], s[18:19]
	ds_read_b128 v[168:171], v244 offset:57344
	ds_read_b128 v[172:175], v244 offset:58368
	ds_read_b128 v[176:179], v244 offset:59392
	ds_read_b128 v[180:183], v244 offset:60416
	ds_read_b128 v[184:187], v244 offset:61440
	global_load_lds_dwordx4 v246, s[8:9]
	s_mov_b32 m0, s43
	ds_read_b128 v[188:191], v244 offset:62464
	global_load_lds_dwordx4 v245, s[8:9]
	s_add_u32 s8, s18, s28
	s_addc_u32 s9, s19, s29
	s_mov_b32 m0, s78
	ds_read_b128 v[192:195], v244 offset:63488
	global_load_lds_dwordx4 v246, s[8:9]
	s_mov_b32 m0, s79
	ds_read_b128 v[196:199], v244 offset:64512
	global_load_lds_dwordx4 v245, s[8:9]
	s_waitcnt vmcnt(6)
	s_waitcnt lgkmcnt(0)
	s_barrier
	s_setprio 1
	s_waitcnt lgkmcnt(0)
	v_mfma_f32_16x16x32_bf16 v[68:71], v[136:139], v[168:171], v[68:71]
	v_mfma_f32_16x16x32_bf16 v[68:71], v[140:143], v[172:175], v[68:71]
	v_mfma_f32_16x16x32_bf16 v[72:75], v[144:147], v[168:171], v[72:75]
	v_mfma_f32_16x16x32_bf16 v[72:75], v[148:151], v[172:175], v[72:75]
	v_mfma_f32_16x16x32_bf16 v[76:79], v[136:139], v[176:179], v[76:79]
	v_mfma_f32_16x16x32_bf16 v[76:79], v[140:143], v[180:183], v[76:79]
	v_mfma_f32_16x16x32_bf16 v[80:83], v[144:147], v[176:179], v[80:83]
	v_mfma_f32_16x16x32_bf16 v[80:83], v[148:151], v[180:183], v[80:83]
	v_mfma_f32_16x16x32_bf16 v[84:87], v[136:139], v[184:187], v[84:87]
	v_mfma_f32_16x16x32_bf16 v[84:87], v[140:143], v[188:191], v[84:87]
	v_mfma_f32_16x16x32_bf16 v[88:91], v[144:147], v[184:187], v[88:91]
	v_mfma_f32_16x16x32_bf16 v[88:91], v[148:151], v[188:191], v[88:91]
	v_mfma_f32_16x16x32_bf16 v[92:95], v[136:139], v[192:195], v[92:95]
	v_mfma_f32_16x16x32_bf16 v[92:95], v[140:143], v[196:199], v[92:95]
	v_mfma_f32_16x16x32_bf16 v[96:99], v[144:147], v[192:195], v[96:99]
	v_mfma_f32_16x16x32_bf16 v[96:99], v[148:151], v[196:199], v[96:99]
	s_setprio 0
	s_setprio 1
	v_mfma_f32_16x16x32_bf16 v[100:103], v[152:155], v[168:171], v[100:103]
	v_mfma_f32_16x16x32_bf16 v[100:103], v[156:159], v[172:175], v[100:103]
	v_mfma_f32_16x16x32_bf16 v[104:107], v[160:163], v[168:171], v[104:107]
	v_mfma_f32_16x16x32_bf16 v[104:107], v[164:167], v[172:175], v[104:107]
	v_mfma_f32_16x16x32_bf16 v[108:111], v[152:155], v[176:179], v[108:111]
	v_mfma_f32_16x16x32_bf16 v[108:111], v[156:159], v[180:183], v[108:111]
	v_mfma_f32_16x16x32_bf16 v[112:115], v[160:163], v[176:179], v[112:115]
	v_mfma_f32_16x16x32_bf16 v[112:115], v[164:167], v[180:183], v[112:115]
	v_mfma_f32_16x16x32_bf16 v[116:119], v[152:155], v[184:187], v[116:119]
	v_mfma_f32_16x16x32_bf16 v[116:119], v[156:159], v[188:191], v[116:119]
	v_mfma_f32_16x16x32_bf16 v[120:123], v[160:163], v[184:187], v[120:123]
	v_mfma_f32_16x16x32_bf16 v[120:123], v[164:167], v[188:191], v[120:123]
	v_mfma_f32_16x16x32_bf16 v[124:127], v[152:155], v[192:195], v[124:127]
	v_mfma_f32_16x16x32_bf16 v[124:127], v[156:159], v[196:199], v[124:127]
	v_mfma_f32_16x16x32_bf16 v[128:131], v[160:163], v[192:195], v[128:131]
	v_mfma_f32_16x16x32_bf16 v[128:131], v[164:167], v[196:199], v[128:131]
	s_setprio 0
	s_barrier
	s_add_i32 s8, s82, 2
	s_add_u32 s80, s80, 0x100
	s_addc_u32 s81, s81, 0
	s_add_u32 s52, s52, 0x100
	s_addc_u32 s53, s53, 0
	s_cmp_ge_i32 s82, s6
	s_mov_b32 s82, s8
	s_cbranch_scc0 .LBB0_1156

.LBB0_1176:
	ds_read_b128 v[136:139], v132
	ds_read_b128 v[140:143], v132 offset:1024
	ds_read_b128 v[144:147], v132 offset:2048
	ds_read_b128 v[148:151], v132 offset:3072
	ds_read_b128 v[152:155], v133
	ds_read_b128 v[156:159], v133 offset:1024
	ds_read_b128 v[160:163], v133 offset:2048
	ds_read_b128 v[164:167], v133 offset:3072
	s_cmp_eq_u32 s6, s80
	s_cselect_b32 s17, s21, s79
	s_cselect_b32 s16, s20, s78
	s_cselect_b32 s27, s41, s51
	s_cselect_b32 s26, s40, s50
	s_add_u32 s8, s50, 0xffffff80
	s_addc_u32 s9, s51, -1
	s_mov_b32 m0, s64
	s_mov_b64 s[18:19], s[8:9]
	ds_read_b128 v[168:171], v244
	ds_read_b128 v[172:175], v244 offset:1024
	ds_read_b128 v[176:179], v244 offset:2048
	ds_read_b128 v[180:183], v244 offset:3072
	ds_read_b128 v[184:187], v244 offset:4096
	ds_read_b128 v[188:191], v244 offset:5120
	ds_read_b128 v[192:195], v244 offset:6144
	ds_read_b128 v[196:199], v244 offset:7168
	s_add_u32 s8, s8, s28
	global_load_lds_dwordx4 v238, s[18:19]
	s_mov_b32 m0, s65
	s_addc_u32 s9, s9, s29
	global_load_lds_dwordx4 v2, s[18:19]
	s_mov_b32 m0, s66
	s_add_u32 s18, s16, 0x80
	global_load_lds_dwordx4 v238, s[8:9]
	s_mov_b32 m0, s67
	s_addc_u32 s19, s17, 0
	global_load_lds_dwordx4 v2, s[8:9]
	s_waitcnt vmcnt(8)
	s_waitcnt lgkmcnt(0)
	s_barrier
	s_setprio 1
	s_waitcnt lgkmcnt(0)
	v_mfma_f32_16x16x32_bf16 v[4:7], v[136:139], v[168:171], v[4:7]
	v_mfma_f32_16x16x32_bf16 v[4:7], v[140:143], v[172:175], v[4:7]
	v_mfma_f32_16x16x32_bf16 v[8:11], v[144:147], v[168:171], v[8:11]
	v_mfma_f32_16x16x32_bf16 v[8:11], v[148:151], v[172:175], v[8:11]
	v_mfma_f32_16x16x32_bf16 v[12:15], v[136:139], v[176:179], v[12:15]
	v_mfma_f32_16x16x32_bf16 v[12:15], v[140:143], v[180:183], v[12:15]
	v_mfma_f32_16x16x32_bf16 v[16:19], v[144:147], v[176:179], v[16:19]
	v_mfma_f32_16x16x32_bf16 v[16:19], v[148:151], v[180:183], v[16:19]
	v_mfma_f32_16x16x32_bf16 v[20:23], v[136:139], v[184:187], v[20:23]
	v_mfma_f32_16x16x32_bf16 v[20:23], v[140:143], v[188:191], v[20:23]
	v_mfma_f32_16x16x32_bf16 v[24:27], v[144:147], v[184:187], v[24:27]
	v_mfma_f32_16x16x32_bf16 v[24:27], v[148:151], v[188:191], v[24:27]
	v_mfma_f32_16x16x32_bf16 v[28:31], v[136:139], v[192:195], v[28:31]
	v_mfma_f32_16x16x32_bf16 v[28:31], v[140:143], v[196:199], v[28:31]
	v_mfma_f32_16x16x32_bf16 v[32:35], v[144:147], v[192:195], v[32:35]
	v_mfma_f32_16x16x32_bf16 v[32:35], v[148:151], v[196:199], v[32:35]
	s_setprio 0
	s_setprio 1
	v_mfma_f32_16x16x32_bf16 v[36:39], v[152:155], v[168:171], v[36:39]
	v_mfma_f32_16x16x32_bf16 v[36:39], v[156:159], v[172:175], v[36:39]
	v_mfma_f32_16x16x32_bf16 v[40:43], v[160:163], v[168:171], v[40:43]
	v_mfma_f32_16x16x32_bf16 v[40:43], v[164:167], v[172:175], v[40:43]
	v_mfma_f32_16x16x32_bf16 v[44:47], v[152:155], v[176:179], v[44:47]
	v_mfma_f32_16x16x32_bf16 v[44:47], v[156:159], v[180:183], v[44:47]
	v_mfma_f32_16x16x32_bf16 v[48:51], v[160:163], v[176:179], v[48:51]
	v_mfma_f32_16x16x32_bf16 v[48:51], v[164:167], v[180:183], v[48:51]
	v_mfma_f32_16x16x32_bf16 v[52:55], v[152:155], v[184:187], v[52:55]
	v_mfma_f32_16x16x32_bf16 v[52:55], v[156:159], v[188:191], v[52:55]
	v_mfma_f32_16x16x32_bf16 v[56:59], v[160:163], v[184:187], v[56:59]
	v_mfma_f32_16x16x32_bf16 v[56:59], v[164:167], v[188:191], v[56:59]
	v_mfma_f32_16x16x32_bf16 v[60:63], v[152:155], v[192:195], v[60:63]
	v_mfma_f32_16x16x32_bf16 v[60:63], v[156:159], v[196:199], v[60:63]
	v_mfma_f32_16x16x32_bf16 v[64:67], v[160:163], v[192:195], v[64:67]
	v_mfma_f32_16x16x32_bf16 v[64:67], v[164:167], v[196:199], v[64:67]
	s_setprio 0
	s_barrier
	s_mov_b32 m0, s68
	s_mov_b64 s[8:9], s[16:17]
	ds_read_b128 v[168:171], v244 offset:16384
	ds_read_b128 v[172:175], v244 offset:17408
	ds_read_b128 v[176:179], v244 offset:18432
	ds_read_b128 v[180:183], v244 offset:19456
	ds_read_b128 v[184:187], v244 offset:20480
	global_load_lds_dwordx4 v246, s[8:9]
	s_mov_b32 m0, s69
	ds_read_b128 v[188:191], v244 offset:21504
	global_load_lds_dwordx4 v245, s[8:9]
	s_add_u32 s8, s16, s28
	s_addc_u32 s9, s17, s29
	s_mov_b32 m0, s72
	ds_read_b128 v[192:195], v244 offset:22528
	global_load_lds_dwordx4 v246, s[8:9]
	s_mov_b32 m0, s73
	ds_read_b128 v[196:199], v244 offset:23552
	global_load_lds_dwordx4 v245, s[8:9]
	s_waitcnt vmcnt(6)
	s_waitcnt lgkmcnt(0)
	s_barrier
	s_setprio 1
	s_waitcnt lgkmcnt(0)
	v_mfma_f32_16x16x32_bf16 v[68:71], v[136:139], v[168:171], v[68:71]
	v_mfma_f32_16x16x32_bf16 v[68:71], v[140:143], v[172:175], v[68:71]
	v_mfma_f32_16x16x32_bf16 v[72:75], v[144:147], v[168:171], v[72:75]
	v_mfma_f32_16x16x32_bf16 v[72:75], v[148:151], v[172:175], v[72:75]
	v_mfma_f32_16x16x32_bf16 v[76:79], v[136:139], v[176:179], v[76:79]
	v_mfma_f32_16x16x32_bf16 v[76:79], v[140:143], v[180:183], v[76:79]
	v_mfma_f32_16x16x32_bf16 v[80:83], v[144:147], v[176:179], v[80:83]
	v_mfma_f32_16x16x32_bf16 v[80:83], v[148:151], v[180:183], v[80:83]
	v_mfma_f32_16x16x32_bf16 v[84:87], v[136:139], v[184:187], v[84:87]
	v_mfma_f32_16x16x32_bf16 v[84:87], v[140:143], v[188:191], v[84:87]
	v_mfma_f32_16x16x32_bf16 v[88:91], v[144:147], v[184:187], v[88:91]
	v_mfma_f32_16x16x32_bf16 v[88:91], v[148:151], v[188:191], v[88:91]
	v_mfma_f32_16x16x32_bf16 v[92:95], v[136:139], v[192:195], v[92:95]
	v_mfma_f32_16x16x32_bf16 v[92:95], v[140:143], v[196:199], v[92:95]
	v_mfma_f32_16x16x32_bf16 v[96:99], v[144:147], v[192:195], v[96:99]
	v_mfma_f32_16x16x32_bf16 v[96:99], v[148:151], v[196:199], v[96:99]
	s_setprio 0
	s_setprio 1
	v_mfma_f32_16x16x32_bf16 v[100:103], v[152:155], v[168:171], v[100:103]
	v_mfma_f32_16x16x32_bf16 v[100:103], v[156:159], v[172:175], v[100:103]
	v_mfma_f32_16x16x32_bf16 v[104:107], v[160:163], v[168:171], v[104:107]
	v_mfma_f32_16x16x32_bf16 v[104:107], v[164:167], v[172:175], v[104:107]
	v_mfma_f32_16x16x32_bf16 v[108:111], v[152:155], v[176:179], v[108:111]
	v_mfma_f32_16x16x32_bf16 v[108:111], v[156:159], v[180:183], v[108:111]
	v_mfma_f32_16x16x32_bf16 v[112:115], v[160:163], v[176:179], v[112:115]
	v_mfma_f32_16x16x32_bf16 v[112:115], v[164:167], v[180:183], v[112:115]
	v_mfma_f32_16x16x32_bf16 v[116:119], v[152:155], v[184:187], v[116:119]
	v_mfma_f32_16x16x32_bf16 v[116:119], v[156:159], v[188:191], v[116:119]
	v_mfma_f32_16x16x32_bf16 v[120:123], v[160:163], v[184:187], v[120:123]
	v_mfma_f32_16x16x32_bf16 v[120:123], v[164:167], v[188:191], v[120:123]
	v_mfma_f32_16x16x32_bf16 v[124:127], v[152:155], v[192:195], v[124:127]
	v_mfma_f32_16x16x32_bf16 v[124:127], v[156:159], v[196:199], v[124:127]
	v_mfma_f32_16x16x32_bf16 v[128:131], v[160:163], v[192:195], v[128:131]
	v_mfma_f32_16x16x32_bf16 v[128:131], v[164:167], v[196:199], v[128:131]
	s_setprio 0
	s_barrier
	ds_read_b128 v[136:139], v134
	ds_read_b128 v[140:143], v134 offset:1024
	ds_read_b128 v[144:147], v134 offset:2048
	ds_read_b128 v[148:151], v134 offset:3072
	ds_read_b128 v[152:155], v135
	ds_read_b128 v[156:159], v135 offset:1024
	ds_read_b128 v[160:163], v135 offset:2048
	ds_read_b128 v[164:167], v135 offset:3072
	s_mov_b32 m0, s53
	s_mov_b64 s[8:9], s[26:27]
	ds_read_b128 v[168:171], v244 offset:32768
	ds_read_b128 v[172:175], v244 offset:33792
	ds_read_b128 v[176:179], v244 offset:34816
	ds_read_b128 v[180:183], v244 offset:35840
	ds_read_b128 v[184:187], v244 offset:36864
	global_load_lds_dwordx4 v238, s[8:9]
	s_mov_b32 m0, s57
	ds_read_b128 v[188:191], v244 offset:37888
	global_load_lds_dwordx4 v2, s[8:9]
	s_add_u32 s8, s26, s28
	s_addc_u32 s9, s27, s29
	s_mov_b32 m0, s58
	ds_read_b128 v[192:195], v244 offset:38912
	global_load_lds_dwordx4 v238, s[8:9]
	s_mov_b32 m0, s59
	ds_read_b128 v[196:199], v244 offset:39936
	global_load_lds_dwordx4 v2, s[8:9]
	s_waitcnt vmcnt(8)
	s_waitcnt lgkmcnt(0)
	s_barrier
	s_setprio 1
	s_waitcnt lgkmcnt(0)
	v_mfma_f32_16x16x32_bf16 v[4:7], v[136:139], v[168:171], v[4:7]
	v_mfma_f32_16x16x32_bf16 v[4:7], v[140:143], v[172:175], v[4:7]
	v_mfma_f32_16x16x32_bf16 v[8:11], v[144:147], v[168:171], v[8:11]
	v_mfma_f32_16x16x32_bf16 v[8:11], v[148:151], v[172:175], v[8:11]
	v_mfma_f32_16x16x32_bf16 v[12:15], v[136:139], v[176:179], v[12:15]
	v_mfma_f32_16x16x32_bf16 v[12:15], v[140:143], v[180:183], v[12:15]
	v_mfma_f32_16x16x32_bf16 v[16:19], v[144:147], v[176:179], v[16:19]
	v_mfma_f32_16x16x32_bf16 v[16:19], v[148:151], v[180:183], v[16:19]
	v_mfma_f32_16x16x32_bf16 v[20:23], v[136:139], v[184:187], v[20:23]
	v_mfma_f32_16x16x32_bf16 v[20:23], v[140:143], v[188:191], v[20:23]
	v_mfma_f32_16x16x32_bf16 v[24:27], v[144:147], v[184:187], v[24:27]
	v_mfma_f32_16x16x32_bf16 v[24:27], v[148:151], v[188:191], v[24:27]
	v_mfma_f32_16x16x32_bf16 v[28:31], v[136:139], v[192:195], v[28:31]
	v_mfma_f32_16x16x32_bf16 v[28:31], v[140:143], v[196:199], v[28:31]
	v_mfma_f32_16x16x32_bf16 v[32:35], v[144:147], v[192:195], v[32:35]
	v_mfma_f32_16x16x32_bf16 v[32:35], v[148:151], v[196:199], v[32:35]
	s_setprio 0
	s_setprio 1
	v_mfma_f32_16x16x32_bf16 v[36:39], v[152:155], v[168:171], v[36:39]
	v_mfma_f32_16x16x32_bf16 v[36:39], v[156:159], v[172:175], v[36:39]
	v_mfma_f32_16x16x32_bf16 v[40:43], v[160:163], v[168:171], v[40:43]
	v_mfma_f32_16x16x32_bf16 v[40:43], v[164:167], v[172:175], v[40:43]
	v_mfma_f32_16x16x32_bf16 v[44:47], v[152:155], v[176:179], v[44:47]
	v_mfma_f32_16x16x32_bf16 v[44:47], v[156:159], v[180:183], v[44:47]
	v_mfma_f32_16x16x32_bf16 v[48:51], v[160:163], v[176:179], v[48:51]
	v_mfma_f32_16x16x32_bf16 v[48:51], v[164:167], v[180:183], v[48:51]
	v_mfma_f32_16x16x32_bf16 v[52:55], v[152:155], v[184:187], v[52:55]
	v_mfma_f32_16x16x32_bf16 v[52:55], v[156:159], v[188:191], v[52:55]
	v_mfma_f32_16x16x32_bf16 v[56:59], v[160:163], v[184:187], v[56:59]
	v_mfma_f32_16x16x32_bf16 v[56:59], v[164:167], v[188:191], v[56:59]
	v_mfma_f32_16x16x32_bf16 v[60:63], v[152:155], v[192:195], v[60:63]
	v_mfma_f32_16x16x32_bf16 v[60:63], v[156:159], v[196:199], v[60:63]
	v_mfma_f32_16x16x32_bf16 v[64:67], v[160:163], v[192:195], v[64:67]
	v_mfma_f32_16x16x32_bf16 v[64:67], v[164:167], v[196:199], v[64:67]
	s_setprio 0
	s_barrier
	s_mov_b32 m0, s42
	s_mov_b64 s[8:9], s[18:19]
	ds_read_b128 v[168:171], v244 offset:49152
	ds_read_b128 v[172:175], v244 offset:50176
	ds_read_b128 v[176:179], v244 offset:51200
	ds_read_b128 v[180:183], v244 offset:52224
	ds_read_b128 v[184:187], v244 offset:53248
	global_load_lds_dwordx4 v246, s[8:9]
	s_mov_b32 m0, s43
	ds_read_b128 v[188:191], v244 offset:54272
	global_load_lds_dwordx4 v245, s[8:9]
	s_add_u32 s8, s18, s28
	s_addc_u32 s9, s19, s29
	s_mov_b32 m0, s76
	ds_read_b128 v[192:195], v244 offset:55296
	global_load_lds_dwordx4 v246, s[8:9]
	s_mov_b32 m0, s77
	ds_read_b128 v[196:199], v244 offset:56320
	global_load_lds_dwordx4 v245, s[8:9]
	s_waitcnt vmcnt(6)
	s_waitcnt lgkmcnt(0)
	s_barrier
	s_setprio 1
	s_waitcnt lgkmcnt(0)
	v_mfma_f32_16x16x32_bf16 v[68:71], v[136:139], v[168:171], v[68:71]
	v_mfma_f32_16x16x32_bf16 v[68:71], v[140:143], v[172:175], v[68:71]
	v_mfma_f32_16x16x32_bf16 v[72:75], v[144:147], v[168:171], v[72:75]
	v_mfma_f32_16x16x32_bf16 v[72:75], v[148:151], v[172:175], v[72:75]
	v_mfma_f32_16x16x32_bf16 v[76:79], v[136:139], v[176:179], v[76:79]
	v_mfma_f32_16x16x32_bf16 v[76:79], v[140:143], v[180:183], v[76:79]
	v_mfma_f32_16x16x32_bf16 v[80:83], v[144:147], v[176:179], v[80:83]
	v_mfma_f32_16x16x32_bf16 v[80:83], v[148:151], v[180:183], v[80:83]
	v_mfma_f32_16x16x32_bf16 v[84:87], v[136:139], v[184:187], v[84:87]
	v_mfma_f32_16x16x32_bf16 v[84:87], v[140:143], v[188:191], v[84:87]
	v_mfma_f32_16x16x32_bf16 v[88:91], v[144:147], v[184:187], v[88:91]
	v_mfma_f32_16x16x32_bf16 v[88:91], v[148:151], v[188:191], v[88:91]
	v_mfma_f32_16x16x32_bf16 v[92:95], v[136:139], v[192:195], v[92:95]
	v_mfma_f32_16x16x32_bf16 v[92:95], v[140:143], v[196:199], v[92:95]
	v_mfma_f32_16x16x32_bf16 v[96:99], v[144:147], v[192:195], v[96:99]
	v_mfma_f32_16x16x32_bf16 v[96:99], v[148:151], v[196:199], v[96:99]
	s_setprio 0
	s_setprio 1
	v_mfma_f32_16x16x32_bf16 v[100:103], v[152:155], v[168:171], v[100:103]
	v_mfma_f32_16x16x32_bf16 v[100:103], v[156:159], v[172:175], v[100:103]
	v_mfma_f32_16x16x32_bf16 v[104:107], v[160:163], v[168:171], v[104:107]
	v_mfma_f32_16x16x32_bf16 v[104:107], v[164:167], v[172:175], v[104:107]
	v_mfma_f32_16x16x32_bf16 v[108:111], v[152:155], v[176:179], v[108:111]
	v_mfma_f32_16x16x32_bf16 v[108:111], v[156:159], v[180:183], v[108:111]
	v_mfma_f32_16x16x32_bf16 v[112:115], v[160:163], v[176:179], v[112:115]
	v_mfma_f32_16x16x32_bf16 v[112:115], v[164:167], v[180:183], v[112:115]
	v_mfma_f32_16x16x32_bf16 v[116:119], v[152:155], v[184:187], v[116:119]
	v_mfma_f32_16x16x32_bf16 v[116:119], v[156:159], v[188:191], v[116:119]
	v_mfma_f32_16x16x32_bf16 v[120:123], v[160:163], v[184:187], v[120:123]
	v_mfma_f32_16x16x32_bf16 v[120:123], v[164:167], v[188:191], v[120:123]
	v_mfma_f32_16x16x32_bf16 v[124:127], v[152:155], v[192:195], v[124:127]
	v_mfma_f32_16x16x32_bf16 v[124:127], v[156:159], v[196:199], v[124:127]
	v_mfma_f32_16x16x32_bf16 v[128:131], v[160:163], v[192:195], v[128:131]
	v_mfma_f32_16x16x32_bf16 v[128:131], v[164:167], v[196:199], v[128:131]
	s_setprio 0
	s_barrier
	s_add_i32 s8, s80, 2
	s_add_u32 s78, s78, 0x100
	s_addc_u32 s79, s79, 0
	s_add_u32 s50, s50, 0x100
	s_addc_u32 s51, s51, 0
	s_cmp_ge_i32 s80, s6
	s_mov_b32 s80, s8
	s_cbranch_scc0 .LBB0_1176
